# v58 + every 32-MFMA run of the three 1BAR loops starts 8-byte aligned (.p2align 3 -> at most one s_nop in front of the run)
# baseline (speedup 1.0000x reference)
; #define PG8_STAGE(bufoff, gbase, voff) do { _Pragma("unroll") for (int _i = 0; _i < 2; ++_i) \
;         __builtin_amdgcn_global_load_lds((const unsigned*)((const char*)(gbase) + (voff)[_i]), (PG8_LAS unsigned*)(lds + (bufoff) + ldsw + _i * 8192), 16, 0, 0); } while (0)
; #define PG8_LDA(dst, b, h) do { _Pragma("unroll") for (int m = 0; m < 4; ++m) _Pragma("unroll") for (int k = 0; k < 2; ++k) dst[m][k] = *(const PG8_LAS bf16x8*)(lds + PG8_SA(b, h) + aoff + m * 2048 + k * 1024); } while (0)
; #define PG8_LDB(dst, b, h) do { _Pragma("unroll") for (int n = 0; n < 2; ++n) _Pragma("unroll") for (int k = 0; k < 2; ++k) dst[n][k] = *(const PG8_LAS bf16x8*)(lds + PG8_SB(b, h) + boff + n * 2048 + k * 1024); } while (0)
; #define PG8_MMA(ai, bj, At, Bt) do { __builtin_amdgcn_s_setprio(1); _Pragma("unroll") for (int m = 0; m < 4; ++m) _Pragma("unroll") for (int n = 0; n < 2; ++n) _Pragma("unroll") for (int k = 0; k < 2; ++k) \
;         acc[ai][bj][m][n] = __builtin_amdgcn_mfma_f32_16x16x32_bf16(Bt[n][k], At[m][k], acc[ai][bj][m][n], 0, 0, 0); __builtin_amdgcn_s_setprio(0); } while (0)
; #define PG8_WAIT_V(n) asm volatile("s_waitcnt vmcnt(" #n ")" ::: "memory")
; template <class Epi, class Sched, bool ALIGN_EPI = false, bool SP2 = false>
; __device__ __forceinline__ void gemm_phase(PG8_LAS unsigned char* lds, const Gemm g, const Sched& S, const Epi& E) {
;     ...
;             PG8_LDB(B0, 0, 0); PG8_LDB(B1, 0, 1); PG8_SCHED; PG8_LDA(At, 0, 0); PG8_STAGE(PG8_SA(1, 1), a1 + hstep, voffA);
;             PG8_WAIT_V(8); PG8_WAIT_L(0); PG8_BAR; PG8_MMA(0, 0, At, B0); PG8_MMA(0, 1, At, B1); PG8_BAR; PG8_SCHED;
;             PG8_LDA(At, 0, 1); PG8_STAGE(PG8_SB(0, 0), b2, voffB); PG8_STAGE(PG8_SB(0, 1), b2 + hstep, voffB); PG8_STAGE(PG8_SA(0, 0), a2, voffA);
;             PG8_WAIT_V(8); PG8_WAIT_L(0); PG8_BAR; PG8_MMA(1, 0, At, B0); PG8_MMA(1, 1, At, B1); PG8_BAR; PG8_SCHED;
;             PG8_LDB(B0, 1, 0); PG8_LDB(B1, 1, 1); PG8_SCHED; PG8_LDA(At, 1, 0); PG8_STAGE(PG8_SA(0, 1), a2 + hstep, voffA);
;             PG8_WAIT_V(8); PG8_WAIT_L(0); PG8_BAR; PG8_MMA(0, 0, At, B0); PG8_MMA(0, 1, At, B1); PG8_BAR; PG8_SCHED;
;             PG8_LDA(At, 1, 1); PG8_STAGE(PG8_SB(1, 0), b3, voffB); PG8_STAGE(PG8_SB(1, 1), b3 + hstep, voffB); PG8_STAGE(PG8_SA(1, 0), a3, voffA);
;             PG8_WAIT_V(8); PG8_WAIT_L(0); PG8_BAR; PG8_MMA(1, 0, At, B0); PG8_MMA(1, 1, At, B1); PG8_BAR; PG8_SCHED;
.LBB0_349:
	ds_read_b128 v[150:153], v169
	ds_read_b128 v[154:157], v169 offset:1024
	ds_read_b128 v[158:161], v169 offset:2048
	ds_read_b128 v[162:165], v169 offset:3072
	ds_read_b128 v[174:177], v170
	ds_read_b128 v[178:181], v170 offset:1024
	ds_read_b128 v[182:185], v170 offset:2048
	ds_read_b128 v[186:189], v170 offset:3072
	s_add_u32 s0, s88, 0xfff00080
	s_addc_u32 s1, s89, -1
	s_cmp_eq_u32 s23, 60
	s_cselect_b32 s93, s51, s1
	s_cselect_b32 s92, s50, s0
	s_cselect_b32 s91, s53, s21
	s_cselect_b32 s90, s52, s9
	ds_read_b128 v[190:193], v171
	ds_read_b128 v[196:199], v171 offset:1024
	ds_read_b128 v[200:203], v171 offset:2048
	ds_read_b128 v[204:207], v171 offset:3072
	ds_read_b128 v[208:211], v171 offset:4096
	ds_read_b128 v[212:215], v171 offset:5120
	ds_read_b128 v[220:223], v171 offset:6144
	ds_read_b128 v[224:227], v171 offset:7168
	s_add_u32 s0, s88, 0xfff00000
	s_addc_u32 s1, s89, -1
	s_add_i32 m0, s27, 0x8000
	s_nop 0
	global_load_lds_dwordx4 v134, s[0:1]
	s_add_i32 m0, s27, 0xa000
	s_nop 0
	global_load_lds_dwordx4 v138, s[0:1]
	s_add_i32 m0, s27, 0xc000
	s_nop 0
	global_load_lds_dwordx4 v134, s[88:89]
	s_add_i32 m0, s27, 0xe000
	s_nop 0
	global_load_lds_dwordx4 v138, s[88:89]
	s_waitcnt lgkmcnt(0)
	s_setprio 1
	.p2align 3
	v_mfma_f32_16x16x32_bf16 v[38:41], v[150:153], v[190:193], v[38:41]
	v_mfma_f32_16x16x32_bf16 v[38:41], v[154:157], v[196:199], v[38:41]
	v_mfma_f32_16x16x32_bf16 v[30:33], v[158:161], v[190:193], v[30:33]
	v_mfma_f32_16x16x32_bf16 v[30:33], v[162:165], v[196:199], v[30:33]
	v_mfma_f32_16x16x32_bf16 v[50:53], v[174:177], v[190:193], v[50:53]
	v_mfma_f32_16x16x32_bf16 v[50:53], v[178:181], v[196:199], v[50:53]
	v_mfma_f32_16x16x32_bf16 v[46:49], v[182:185], v[190:193], v[46:49]
	v_mfma_f32_16x16x32_bf16 v[46:49], v[186:189], v[196:199], v[46:49]
	v_mfma_f32_16x16x32_bf16 v[118:121], v[182:185], v[200:203], v[118:121]
	v_mfma_f32_16x16x32_bf16 v[118:121], v[186:189], v[204:207], v[118:121]
	v_mfma_f32_16x16x32_bf16 v[122:125], v[174:177], v[200:203], v[122:125]
	v_mfma_f32_16x16x32_bf16 v[122:125], v[178:181], v[204:207], v[122:125]
	v_mfma_f32_16x16x32_bf16 v[126:129], v[158:161], v[200:203], v[126:129]
	v_mfma_f32_16x16x32_bf16 v[126:129], v[162:165], v[204:207], v[126:129]
	v_mfma_f32_16x16x32_bf16 v[130:133], v[150:153], v[200:203], v[130:133]
	v_mfma_f32_16x16x32_bf16 v[130:133], v[154:157], v[204:207], v[130:133]
	v_mfma_f32_16x16x32_bf16 v[114:117], v[150:153], v[208:211], v[114:117]
	v_mfma_f32_16x16x32_bf16 v[114:117], v[154:157], v[212:215], v[114:117]
	v_mfma_f32_16x16x32_bf16 v[110:113], v[158:161], v[208:211], v[110:113]
	v_mfma_f32_16x16x32_bf16 v[110:113], v[162:165], v[212:215], v[110:113]
	v_mfma_f32_16x16x32_bf16 v[106:109], v[174:177], v[208:211], v[106:109]
	v_mfma_f32_16x16x32_bf16 v[106:109], v[178:181], v[212:215], v[106:109]
	v_mfma_f32_16x16x32_bf16 v[102:105], v[182:185], v[208:211], v[102:105]
	v_mfma_f32_16x16x32_bf16 v[102:105], v[186:189], v[212:215], v[102:105]
	v_mfma_f32_16x16x32_bf16 v[86:89], v[182:185], v[220:223], v[86:89]
	v_mfma_f32_16x16x32_bf16 v[86:89], v[186:189], v[224:227], v[86:89]
	v_mfma_f32_16x16x32_bf16 v[90:93], v[174:177], v[220:223], v[90:93]
	v_mfma_f32_16x16x32_bf16 v[90:93], v[178:181], v[224:227], v[90:93]
	v_mfma_f32_16x16x32_bf16 v[94:97], v[158:161], v[220:223], v[94:97]
	v_mfma_f32_16x16x32_bf16 v[94:97], v[162:165], v[224:227], v[94:97]
	v_mfma_f32_16x16x32_bf16 v[98:101], v[150:153], v[220:223], v[98:101]
	v_mfma_f32_16x16x32_bf16 v[98:101], v[154:157], v[224:227], v[98:101]
	s_setprio 0
	s_waitcnt vmcnt(8)
	s_barrier
	ds_read_b128 v[190:193], v171 offset:16384
	ds_read_b128 v[196:199], v171 offset:17408
	ds_read_b128 v[200:203], v171 offset:18432
	ds_read_b128 v[204:207], v171 offset:19456
	ds_read_b128 v[208:211], v171 offset:20480
	ds_read_b128 v[212:215], v171 offset:21504
	ds_read_b128 v[220:223], v171 offset:22528
	ds_read_b128 v[224:227], v171 offset:23552
	s_add_u32 vcc_lo, s90, 0x100000
	s_addc_u32 vcc_hi, s91, 0
	s_add_i32 m0, s27, 0x10000
	s_nop 0
	global_load_lds_dwordx4 v136, s[90:91]
	s_add_i32 m0, s27, 0x12000
	s_nop 0
	global_load_lds_dwordx4 v140, s[90:91]
	s_add_i32 m0, s27, 0x14000
	s_nop 0
	global_load_lds_dwordx4 v136, vcc
	s_add_i32 m0, s27, 0x16000
	s_nop 0
	global_load_lds_dwordx4 v140, vcc
	s_waitcnt lgkmcnt(0)
	s_setprio 1
	.p2align 3
	v_mfma_f32_16x16x32_bf16 v[82:85], v[150:153], v[190:193], v[82:85]
	v_mfma_f32_16x16x32_bf16 v[82:85], v[154:157], v[196:199], v[82:85]
	v_mfma_f32_16x16x32_bf16 v[78:81], v[158:161], v[190:193], v[78:81]
	v_mfma_f32_16x16x32_bf16 v[78:81], v[162:165], v[196:199], v[78:81]
	v_mfma_f32_16x16x32_bf16 v[74:77], v[174:177], v[190:193], v[74:77]
	v_mfma_f32_16x16x32_bf16 v[74:77], v[178:181], v[196:199], v[74:77]
	v_mfma_f32_16x16x32_bf16 v[70:73], v[182:185], v[190:193], v[70:73]
	v_mfma_f32_16x16x32_bf16 v[70:73], v[186:189], v[196:199], v[70:73]
	v_mfma_f32_16x16x32_bf16 v[54:57], v[182:185], v[200:203], v[54:57]
	v_mfma_f32_16x16x32_bf16 v[54:57], v[186:189], v[204:207], v[54:57]
	v_mfma_f32_16x16x32_bf16 v[58:61], v[174:177], v[200:203], v[58:61]
	v_mfma_f32_16x16x32_bf16 v[58:61], v[178:181], v[204:207], v[58:61]
	v_mfma_f32_16x16x32_bf16 v[62:65], v[158:161], v[200:203], v[62:65]
	v_mfma_f32_16x16x32_bf16 v[62:65], v[162:165], v[204:207], v[62:65]
	v_mfma_f32_16x16x32_bf16 v[66:69], v[150:153], v[200:203], v[66:69]
	v_mfma_f32_16x16x32_bf16 v[66:69], v[154:157], v[204:207], v[66:69]
	v_mfma_f32_16x16x32_bf16 v[42:45], v[150:153], v[208:211], v[42:45]
	v_mfma_f32_16x16x32_bf16 v[42:45], v[154:157], v[212:215], v[42:45]
	v_mfma_f32_16x16x32_bf16 v[34:37], v[158:161], v[208:211], v[34:37]
	v_mfma_f32_16x16x32_bf16 v[34:37], v[162:165], v[212:215], v[34:37]
	v_mfma_f32_16x16x32_bf16 v[26:29], v[174:177], v[208:211], v[26:29]
	v_mfma_f32_16x16x32_bf16 v[26:29], v[178:181], v[212:215], v[26:29]
	v_mfma_f32_16x16x32_bf16 v[22:25], v[182:185], v[208:211], v[22:25]
	v_mfma_f32_16x16x32_bf16 v[22:25], v[186:189], v[212:215], v[22:25]
	v_mfma_f32_16x16x32_bf16 v[4:7], v[182:185], v[220:223], v[6:9]
	v_mfma_f32_16x16x32_bf16 v[4:7], v[186:189], v[224:227], v[4:7]
	v_mfma_f32_16x16x32_bf16 v[10:13], v[174:177], v[220:223], v[10:13]
	v_mfma_f32_16x16x32_bf16 v[10:13], v[178:181], v[224:227], v[10:13]
	v_mfma_f32_16x16x32_bf16 v[14:17], v[158:161], v[220:223], v[14:17]
	v_mfma_f32_16x16x32_bf16 v[14:17], v[162:165], v[224:227], v[14:17]
	v_mfma_f32_16x16x32_bf16 v[18:21], v[150:153], v[220:223], v[18:21]
	v_mfma_f32_16x16x32_bf16 v[18:21], v[154:157], v[224:227], v[18:21]
	s_setprio 0
	s_waitcnt vmcnt(6)
	s_barrier
; #define PG8_STAGE(bufoff, gbase, voff) do { _Pragma("unroll") for (int _i = 0; _i < 2; ++_i) \
;         __builtin_amdgcn_global_load_lds((const unsigned*)((const char*)(gbase) + (voff)[_i]), (PG8_LAS unsigned*)(lds + (bufoff) + ldsw + _i * 8192), 16, 0, 0); } while (0)
; #define PG8_LDA(dst, b, h) do { _Pragma("unroll") for (int m = 0; m < 4; ++m) _Pragma("unroll") for (int k = 0; k < 2; ++k) dst[m][k] = *(const PG8_LAS bf16x8*)(lds + PG8_SA(b, h) + aoff + m * 2048 + k * 1024); } while (0)
; #define PG8_LDB(dst, b, h) do { _Pragma("unroll") for (int n = 0; n < 2; ++n) _Pragma("unroll") for (int k = 0; k < 2; ++k) dst[n][k] = *(const PG8_LAS bf16x8*)(lds + PG8_SB(b, h) + boff + n * 2048 + k * 1024); } while (0)
; #define PG8_MMA(ai, bj, At, Bt) do { __builtin_amdgcn_s_setprio(1); _Pragma("unroll") for (int m = 0; m < 4; ++m) _Pragma("unroll") for (int n = 0; n < 2; ++n) _Pragma("unroll") for (int k = 0; k < 2; ++k) \
;         acc[ai][bj][m][n] = __builtin_amdgcn_mfma_f32_16x16x32_bf16(Bt[n][k], At[m][k], acc[ai][bj][m][n], 0, 0, 0); __builtin_amdgcn_s_setprio(0); } while (0)
; #define PG8_WAIT_V(n) asm volatile("s_waitcnt vmcnt(" #n ")" ::: "memory")
; #define PG8_WAIT_L(n) asm volatile("s_waitcnt lgkmcnt(" #n ")" ::: "memory")
; #define PG8_BAR __builtin_amdgcn_s_barrier()
; #define PG8_SCHED __builtin_amdgcn_sched_barrier(0)
; template <class Epi, class Sched, bool ALIGN_EPI = false, bool SP2 = false>
; __device__ __forceinline__ void gemm_phase(PG8_LAS unsigned char* lds, const Gemm g, const Sched& S, const Epi& E) {
;     ...
;         for (int t = 0; t < nt; t += 2) {
;             const bool last = (t == nt - 2);
;     ...
;             PG8_LDB(B0, 1, 0); PG8_LDB(B1, 1, 1); PG8_SCHED; PG8_LDA(At, 1, 0); PG8_STAGE(PG8_SA(0, 1), a2 + hstep, voffA);
;             PG8_WAIT_V(8); PG8_WAIT_L(0); PG8_BAR; PG8_MMA(0, 0, At, B0); PG8_MMA(0, 1, At, B1); PG8_BAR; PG8_SCHED;
;             PG8_LDA(At, 1, 1); PG8_STAGE(PG8_SB(1, 0), b3, voffB); PG8_STAGE(PG8_SB(1, 1), b3 + hstep, voffB); PG8_STAGE(PG8_SA(1, 0), a3, voffA);
;             PG8_WAIT_V(8); PG8_WAIT_L(0); PG8_BAR; PG8_MMA(1, 0, At, B0); PG8_MMA(1, 1, At, B1); PG8_BAR; PG8_SCHED;
	s_add_i32 s0, 0, 0x18000
	v_add_u32_e32 v3, s0, v167
	s_add_i32 s1, 0, 0x1c000
	ds_read_b128 v[150:153], v3
	ds_read_b128 v[154:157], v3 offset:1024
	ds_read_b128 v[158:161], v3 offset:2048
	ds_read_b128 v[162:165], v3 offset:3072
	v_add_u32_e32 v3, s1, v167
	ds_read_b128 v[174:177], v3
	ds_read_b128 v[178:181], v3 offset:1024
	ds_read_b128 v[182:185], v3 offset:2048
	ds_read_b128 v[186:189], v3 offset:3072
	ds_read_b128 v[190:193], v171 offset:32768
	ds_read_b128 v[196:199], v171 offset:33792
	ds_read_b128 v[200:203], v171 offset:34816
	ds_read_b128 v[204:207], v171 offset:35840
	ds_read_b128 v[208:211], v171 offset:36864
	ds_read_b128 v[212:215], v171 offset:37888
	ds_read_b128 v[220:223], v171 offset:38912
	ds_read_b128 v[224:227], v171 offset:39936
	s_add_u32 vcc_lo, s92, 0x100000
	s_addc_u32 vcc_hi, s93, 0
	s_mov_b32 m0, s27
	s_nop 0
	global_load_lds_dwordx4 v134, s[92:93]
	s_add_i32 m0, s27, 0x2000
	s_nop 0
	global_load_lds_dwordx4 v138, s[92:93]
	s_add_i32 m0, s27, 0x4000
	s_nop 0
	global_load_lds_dwordx4 v134, vcc
	s_add_i32 m0, s27, 0x6000
	s_nop 0
	global_load_lds_dwordx4 v138, vcc
	s_waitcnt lgkmcnt(0)
	s_setprio 1
	.p2align 3
	v_mfma_f32_16x16x32_bf16 v[38:41], v[150:153], v[190:193], v[38:41]
	v_mfma_f32_16x16x32_bf16 v[38:41], v[154:157], v[196:199], v[38:41]
	v_mfma_f32_16x16x32_bf16 v[30:33], v[158:161], v[190:193], v[30:33]
	v_mfma_f32_16x16x32_bf16 v[30:33], v[162:165], v[196:199], v[30:33]
	v_mfma_f32_16x16x32_bf16 v[50:53], v[174:177], v[190:193], v[50:53]
	v_mfma_f32_16x16x32_bf16 v[50:53], v[178:181], v[196:199], v[50:53]
	v_mfma_f32_16x16x32_bf16 v[46:49], v[182:185], v[190:193], v[46:49]
	v_mfma_f32_16x16x32_bf16 v[46:49], v[186:189], v[196:199], v[46:49]
	v_mfma_f32_16x16x32_bf16 v[118:121], v[182:185], v[200:203], v[118:121]
	v_mfma_f32_16x16x32_bf16 v[118:121], v[186:189], v[204:207], v[118:121]
	v_mfma_f32_16x16x32_bf16 v[122:125], v[174:177], v[200:203], v[122:125]
	v_mfma_f32_16x16x32_bf16 v[122:125], v[178:181], v[204:207], v[122:125]
	v_mfma_f32_16x16x32_bf16 v[126:129], v[158:161], v[200:203], v[126:129]
	v_mfma_f32_16x16x32_bf16 v[126:129], v[162:165], v[204:207], v[126:129]
	v_mfma_f32_16x16x32_bf16 v[130:133], v[150:153], v[200:203], v[130:133]
	v_mfma_f32_16x16x32_bf16 v[130:133], v[154:157], v[204:207], v[130:133]
	v_mfma_f32_16x16x32_bf16 v[114:117], v[150:153], v[208:211], v[114:117]
	v_mfma_f32_16x16x32_bf16 v[114:117], v[154:157], v[212:215], v[114:117]
	v_mfma_f32_16x16x32_bf16 v[110:113], v[158:161], v[208:211], v[110:113]
	v_mfma_f32_16x16x32_bf16 v[110:113], v[162:165], v[212:215], v[110:113]
	v_mfma_f32_16x16x32_bf16 v[106:109], v[174:177], v[208:211], v[106:109]
	v_mfma_f32_16x16x32_bf16 v[106:109], v[178:181], v[212:215], v[106:109]
	v_mfma_f32_16x16x32_bf16 v[102:105], v[182:185], v[208:211], v[102:105]
	v_mfma_f32_16x16x32_bf16 v[102:105], v[186:189], v[212:215], v[102:105]
	v_mfma_f32_16x16x32_bf16 v[86:89], v[182:185], v[220:223], v[86:89]
	v_mfma_f32_16x16x32_bf16 v[86:89], v[186:189], v[224:227], v[86:89]
	v_mfma_f32_16x16x32_bf16 v[90:93], v[174:177], v[220:223], v[90:93]
	v_mfma_f32_16x16x32_bf16 v[90:93], v[178:181], v[224:227], v[90:93]
	v_mfma_f32_16x16x32_bf16 v[94:97], v[158:161], v[220:223], v[94:97]
	v_mfma_f32_16x16x32_bf16 v[94:97], v[162:165], v[224:227], v[94:97]
	v_mfma_f32_16x16x32_bf16 v[98:101], v[150:153], v[220:223], v[98:101]
	v_mfma_f32_16x16x32_bf16 v[98:101], v[154:157], v[224:227], v[98:101]
	s_setprio 0
	s_waitcnt vmcnt(8)
	s_barrier
	ds_read_b128 v[190:193], v171 offset:49152
	ds_read_b128 v[196:199], v171 offset:50176
	ds_read_b128 v[200:203], v171 offset:51200
	ds_read_b128 v[204:207], v171 offset:52224
	ds_read_b128 v[208:211], v171 offset:53248
	ds_read_b128 v[212:215], v171 offset:54272
	ds_read_b128 v[220:223], v171 offset:55296
	ds_read_b128 v[224:227], v171 offset:56320
	s_add_u32 s0, s90, 0x80
	s_addc_u32 s1, s91, 0
	s_add_u32 vcc_lo, s0, 0x100000
	s_addc_u32 vcc_hi, s1, 0
	s_add_i32 m0, s27, 0x18000
	s_nop 0
	global_load_lds_dwordx4 v136, s[0:1]
	s_add_i32 m0, s27, 0x1a000
	s_nop 0
	global_load_lds_dwordx4 v140, s[0:1]
	s_add_i32 m0, s27, 0x1c000
	s_nop 0
	global_load_lds_dwordx4 v136, vcc
	s_add_i32 m0, s27, 0x1e000
	s_nop 0
	global_load_lds_dwordx4 v140, vcc
	s_waitcnt lgkmcnt(0)
	s_setprio 1
	.p2align 3
	v_mfma_f32_16x16x32_bf16 v[70:73], v[182:185], v[190:193], v[70:73]
	v_mfma_f32_16x16x32_bf16 v[70:73], v[186:189], v[196:199], v[70:73]
	v_mfma_f32_16x16x32_bf16 v[74:77], v[174:177], v[190:193], v[74:77]
	v_mfma_f32_16x16x32_bf16 v[74:77], v[178:181], v[196:199], v[74:77]
	v_mfma_f32_16x16x32_bf16 v[78:81], v[158:161], v[190:193], v[78:81]
	v_mfma_f32_16x16x32_bf16 v[78:81], v[162:165], v[196:199], v[78:81]
	v_mfma_f32_16x16x32_bf16 v[82:85], v[150:153], v[190:193], v[82:85]
	v_mfma_f32_16x16x32_bf16 v[82:85], v[154:157], v[196:199], v[82:85]
	v_mfma_f32_16x16x32_bf16 v[66:69], v[150:153], v[200:203], v[66:69]
	v_mfma_f32_16x16x32_bf16 v[66:69], v[154:157], v[204:207], v[66:69]
	v_mfma_f32_16x16x32_bf16 v[62:65], v[158:161], v[200:203], v[62:65]
	v_mfma_f32_16x16x32_bf16 v[62:65], v[162:165], v[204:207], v[62:65]
	v_mfma_f32_16x16x32_bf16 v[58:61], v[174:177], v[200:203], v[58:61]
	v_mfma_f32_16x16x32_bf16 v[58:61], v[178:181], v[204:207], v[58:61]
	v_mfma_f32_16x16x32_bf16 v[54:57], v[182:185], v[200:203], v[54:57]
	v_mfma_f32_16x16x32_bf16 v[54:57], v[186:189], v[204:207], v[54:57]
	v_mfma_f32_16x16x32_bf16 v[22:25], v[182:185], v[208:211], v[22:25]
	v_mfma_f32_16x16x32_bf16 v[22:25], v[186:189], v[212:215], v[22:25]
	v_mfma_f32_16x16x32_bf16 v[26:29], v[174:177], v[208:211], v[26:29]
	v_mfma_f32_16x16x32_bf16 v[26:29], v[178:181], v[212:215], v[26:29]
	v_mfma_f32_16x16x32_bf16 v[34:37], v[158:161], v[208:211], v[34:37]
	v_mfma_f32_16x16x32_bf16 v[34:37], v[162:165], v[212:215], v[34:37]
	v_mfma_f32_16x16x32_bf16 v[42:45], v[150:153], v[208:211], v[42:45]
	v_mfma_f32_16x16x32_bf16 v[42:45], v[154:157], v[212:215], v[42:45]
	v_mfma_f32_16x16x32_bf16 v[18:21], v[150:153], v[220:223], v[18:21]
	v_mfma_f32_16x16x32_bf16 v[18:21], v[154:157], v[224:227], v[18:21]
	v_mfma_f32_16x16x32_bf16 v[14:17], v[158:161], v[220:223], v[14:17]
	v_mfma_f32_16x16x32_bf16 v[14:17], v[162:165], v[224:227], v[14:17]
	v_mfma_f32_16x16x32_bf16 v[8:11], v[174:177], v[220:223], v[10:13]
	v_mfma_f32_16x16x32_bf16 v[10:13], v[178:181], v[224:227], v[8:11]
	v_mfma_f32_16x16x32_bf16 v[4:7], v[182:185], v[220:223], v[4:7]
	v_mfma_f32_16x16x32_bf16 v[6:9], v[186:189], v[224:227], v[4:7]
	s_setprio 0
	s_waitcnt vmcnt(6)
	s_barrier
	s_add_i32 s23, s23, 2
	s_add_u32 s88, s88, 0x100
	s_addc_u32 s89, s89, 0
	s_add_u32 s9, s9, 0x100
	s_addc_u32 s21, s21, 0
	s_cmp_gt_u32 s23, 61
	s_cbranch_scc0 .LBB0_349
	s_branch .Lip_exit
; #define PG8_STAGE(bufoff, gbase, voff) do { _Pragma("unroll") for (int _i = 0; _i < 2; ++_i) \
;         __builtin_amdgcn_global_load_lds((const unsigned*)((const char*)(gbase) + (voff)[_i]), (PG8_LAS unsigned*)(lds + (bufoff) + ldsw + _i * 8192), 16, 0, 0); } while (0)
; #define PG8_LDA(dst, b, h) do { _Pragma("unroll") for (int m = 0; m < 4; ++m) _Pragma("unroll") for (int k = 0; k < 2; ++k) dst[m][k] = *(const PG8_LAS bf16x8*)(lds + PG8_SA(b, h) + aoff + m * 2048 + k * 1024); } while (0)
; #define PG8_LDB(dst, b, h) do { _Pragma("unroll") for (int n = 0; n < 2; ++n) _Pragma("unroll") for (int k = 0; k < 2; ++k) dst[n][k] = *(const PG8_LAS bf16x8*)(lds + PG8_SB(b, h) + boff + n * 2048 + k * 1024); } while (0)
; #define PG8_MMA(ai, bj, At, Bt) do { __builtin_amdgcn_s_setprio(1); _Pragma("unroll") for (int m = 0; m < 4; ++m) _Pragma("unroll") for (int n = 0; n < 2; ++n) _Pragma("unroll") for (int k = 0; k < 2; ++k) \
;         acc[ai][bj][m][n] = __builtin_amdgcn_mfma_f32_16x16x32_bf16(Bt[n][k], At[m][k], acc[ai][bj][m][n], 0, 0, 0); __builtin_amdgcn_s_setprio(0); } while (0)
; #define PG8_WAIT_V(n) asm volatile("s_waitcnt vmcnt(" #n ")" ::: "memory")
; #define PG8_WAIT_L(n) asm volatile("s_waitcnt lgkmcnt(" #n ")" ::: "memory")
; #define PG8_BAR __builtin_amdgcn_s_barrier()
; #define PG8_SCHED __builtin_amdgcn_sched_barrier(0)
; template <class Epi, class Sched, bool ALIGN_EPI = false, bool SP2 = false>
; __device__ __forceinline__ void gemm_phase(PG8_LAS unsigned char* lds, const Gemm g, const Sched& S, const Epi& E) {
;     ...
;             PG8_LDB(B0, 0, 0); PG8_LDB(B1, 0, 1); PG8_SCHED; PG8_LDA(At, 0, 0); PG8_STAGE(PG8_SA(1, 1), a1 + hstep, voffA);
;             PG8_WAIT_V(8); PG8_WAIT_L(0); PG8_BAR; PG8_MMA(0, 0, At, B0); PG8_MMA(0, 1, At, B1); PG8_BAR; PG8_SCHED;
;             PG8_LDA(At, 0, 1); PG8_STAGE(PG8_SB(0, 0), b2, voffB); PG8_STAGE(PG8_SB(0, 1), b2 + hstep, voffB); PG8_STAGE(PG8_SA(0, 0), a2, voffA);
;             PG8_WAIT_V(8); PG8_WAIT_L(0); PG8_BAR; PG8_MMA(1, 0, At, B0); PG8_MMA(1, 1, At, B1); PG8_BAR; PG8_SCHED;
.Lip_h1:
	ds_read_b128 v[150:153], v169
	ds_read_b128 v[154:157], v169 offset:1024
	ds_read_b128 v[158:161], v169 offset:2048
	ds_read_b128 v[162:165], v169 offset:3072
	ds_read_b128 v[174:177], v170
	ds_read_b128 v[178:181], v170 offset:1024
	ds_read_b128 v[182:185], v170 offset:2048
	ds_read_b128 v[186:189], v170 offset:3072
	s_add_u32 s0, s88, 0xfff00080
	s_addc_u32 s1, s89, -1
	s_cmp_eq_u32 s23, 60
	s_cselect_b32 s93, s51, s1
	s_cselect_b32 s92, s50, s0
	s_cselect_b32 s91, s53, s21
	s_cselect_b32 s90, s52, s9
	ds_read_b128 v[190:193], v171
	ds_read_b128 v[196:199], v171 offset:1024
	ds_read_b128 v[200:203], v171 offset:2048
	ds_read_b128 v[204:207], v171 offset:3072
	ds_read_b128 v[208:211], v171 offset:4096
	ds_read_b128 v[212:215], v171 offset:5120
	ds_read_b128 v[220:223], v171 offset:6144
	ds_read_b128 v[224:227], v171 offset:7168
	s_add_u32 s0, s88, 0xfff00000
	s_addc_u32 s1, s89, -1
	s_add_i32 m0, s27, 0x8000
	s_nop 0
	global_load_lds_dwordx4 v134, s[0:1]
	s_add_i32 m0, s27, 0xa000
	s_nop 0
	global_load_lds_dwordx4 v138, s[0:1]
	s_add_i32 m0, s27, 0xc000
	s_nop 0
	global_load_lds_dwordx4 v134, s[88:89]
	s_add_i32 m0, s27, 0xe000
	s_nop 0
	global_load_lds_dwordx4 v138, s[88:89]
	s_sleep 2
	s_waitcnt lgkmcnt(0)
	s_waitcnt vmcnt(8)
	s_barrier
	s_setprio 2
	.p2align 3
	v_mfma_f32_16x16x32_bf16 v[38:41], v[150:153], v[190:193], v[38:41]
	v_mfma_f32_16x16x32_bf16 v[38:41], v[154:157], v[196:199], v[38:41]
	v_mfma_f32_16x16x32_bf16 v[30:33], v[158:161], v[190:193], v[30:33]
	v_mfma_f32_16x16x32_bf16 v[30:33], v[162:165], v[196:199], v[30:33]
	v_mfma_f32_16x16x32_bf16 v[50:53], v[174:177], v[190:193], v[50:53]
	v_mfma_f32_16x16x32_bf16 v[50:53], v[178:181], v[196:199], v[50:53]
	v_mfma_f32_16x16x32_bf16 v[46:49], v[182:185], v[190:193], v[46:49]
	v_mfma_f32_16x16x32_bf16 v[46:49], v[186:189], v[196:199], v[46:49]
	v_mfma_f32_16x16x32_bf16 v[118:121], v[182:185], v[200:203], v[118:121]
	v_mfma_f32_16x16x32_bf16 v[118:121], v[186:189], v[204:207], v[118:121]
	v_mfma_f32_16x16x32_bf16 v[122:125], v[174:177], v[200:203], v[122:125]
	v_mfma_f32_16x16x32_bf16 v[122:125], v[178:181], v[204:207], v[122:125]
	v_mfma_f32_16x16x32_bf16 v[126:129], v[158:161], v[200:203], v[126:129]
	v_mfma_f32_16x16x32_bf16 v[126:129], v[162:165], v[204:207], v[126:129]
	v_mfma_f32_16x16x32_bf16 v[130:133], v[150:153], v[200:203], v[130:133]
	v_mfma_f32_16x16x32_bf16 v[130:133], v[154:157], v[204:207], v[130:133]
	v_mfma_f32_16x16x32_bf16 v[114:117], v[150:153], v[208:211], v[114:117]
	v_mfma_f32_16x16x32_bf16 v[114:117], v[154:157], v[212:215], v[114:117]
	v_mfma_f32_16x16x32_bf16 v[110:113], v[158:161], v[208:211], v[110:113]
	v_mfma_f32_16x16x32_bf16 v[110:113], v[162:165], v[212:215], v[110:113]
	v_mfma_f32_16x16x32_bf16 v[106:109], v[174:177], v[208:211], v[106:109]
	v_mfma_f32_16x16x32_bf16 v[106:109], v[178:181], v[212:215], v[106:109]
	v_mfma_f32_16x16x32_bf16 v[102:105], v[182:185], v[208:211], v[102:105]
	v_mfma_f32_16x16x32_bf16 v[102:105], v[186:189], v[212:215], v[102:105]
	v_mfma_f32_16x16x32_bf16 v[86:89], v[182:185], v[220:223], v[86:89]
	v_mfma_f32_16x16x32_bf16 v[86:89], v[186:189], v[224:227], v[86:89]
	v_mfma_f32_16x16x32_bf16 v[90:93], v[174:177], v[220:223], v[90:93]
	v_mfma_f32_16x16x32_bf16 v[90:93], v[178:181], v[224:227], v[90:93]
	v_mfma_f32_16x16x32_bf16 v[94:97], v[158:161], v[220:223], v[94:97]
	v_mfma_f32_16x16x32_bf16 v[94:97], v[162:165], v[224:227], v[94:97]
	v_mfma_f32_16x16x32_bf16 v[98:101], v[150:153], v[220:223], v[98:101]
	v_mfma_f32_16x16x32_bf16 v[98:101], v[154:157], v[224:227], v[98:101]
	s_setprio 0
	ds_read_b128 v[190:193], v171 offset:16384
	ds_read_b128 v[196:199], v171 offset:17408
	ds_read_b128 v[200:203], v171 offset:18432
	ds_read_b128 v[204:207], v171 offset:19456
	ds_read_b128 v[208:211], v171 offset:20480
	ds_read_b128 v[212:215], v171 offset:21504
	ds_read_b128 v[220:223], v171 offset:22528
	ds_read_b128 v[224:227], v171 offset:23552
	s_add_u32 vcc_lo, s90, 0x100000
	s_addc_u32 vcc_hi, s91, 0
	s_add_i32 m0, s27, 0x10000
	s_nop 0
	global_load_lds_dwordx4 v136, s[90:91]
	s_add_i32 m0, s27, 0x12000
	s_nop 0
	global_load_lds_dwordx4 v140, s[90:91]
	s_add_i32 m0, s27, 0x14000
	s_nop 0
	global_load_lds_dwordx4 v136, vcc
	s_add_i32 m0, s27, 0x16000
	s_nop 0
	global_load_lds_dwordx4 v140, vcc
	s_sleep 2
	s_waitcnt lgkmcnt(0)
	s_waitcnt vmcnt(6)
	s_barrier
; #define PG8_STAGE(bufoff, gbase, voff) do { _Pragma("unroll") for (int _i = 0; _i < 2; ++_i) \
;         __builtin_amdgcn_global_load_lds((const unsigned*)((const char*)(gbase) + (voff)[_i]), (PG8_LAS unsigned*)(lds + (bufoff) + ldsw + _i * 8192), 16, 0, 0); } while (0)
; #define PG8_LDA(dst, b, h) do { _Pragma("unroll") for (int m = 0; m < 4; ++m) _Pragma("unroll") for (int k = 0; k < 2; ++k) dst[m][k] = *(const PG8_LAS bf16x8*)(lds + PG8_SA(b, h) + aoff + m * 2048 + k * 1024); } while (0)
; #define PG8_LDB(dst, b, h) do { _Pragma("unroll") for (int n = 0; n < 2; ++n) _Pragma("unroll") for (int k = 0; k < 2; ++k) dst[n][k] = *(const PG8_LAS bf16x8*)(lds + PG8_SB(b, h) + boff + n * 2048 + k * 1024); } while (0)
; #define PG8_MMA(ai, bj, At, Bt) do { __builtin_amdgcn_s_setprio(1); _Pragma("unroll") for (int m = 0; m < 4; ++m) _Pragma("unroll") for (int n = 0; n < 2; ++n) _Pragma("unroll") for (int k = 0; k < 2; ++k) \
;         acc[ai][bj][m][n] = __builtin_amdgcn_mfma_f32_16x16x32_bf16(Bt[n][k], At[m][k], acc[ai][bj][m][n], 0, 0, 0); __builtin_amdgcn_s_setprio(0); } while (0)
; #define PG8_WAIT_V(n) asm volatile("s_waitcnt vmcnt(" #n ")" ::: "memory")
; #define PG8_WAIT_L(n) asm volatile("s_waitcnt lgkmcnt(" #n ")" ::: "memory")
; #define PG8_BAR __builtin_amdgcn_s_barrier()
; #define PG8_SCHED __builtin_amdgcn_sched_barrier(0)
; template <class Epi, class Sched, bool ALIGN_EPI = false, bool SP2 = false>
; __device__ __forceinline__ void gemm_phase(PG8_LAS unsigned char* lds, const Gemm g, const Sched& S, const Epi& E) {
;     ...
;             PG8_WAIT_V(8); PG8_WAIT_L(0); PG8_BAR; PG8_MMA(1, 0, At, B0); PG8_MMA(1, 1, At, B1); PG8_BAR; PG8_SCHED;
;             PG8_LDB(B0, 1, 0); PG8_LDB(B1, 1, 1); PG8_SCHED; PG8_LDA(At, 1, 0); PG8_STAGE(PG8_SA(0, 1), a2 + hstep, voffA);
	s_setprio 2
	.p2align 3
	v_mfma_f32_16x16x32_bf16 v[82:85], v[150:153], v[190:193], v[82:85]
	v_mfma_f32_16x16x32_bf16 v[82:85], v[154:157], v[196:199], v[82:85]
	v_mfma_f32_16x16x32_bf16 v[78:81], v[158:161], v[190:193], v[78:81]
	v_mfma_f32_16x16x32_bf16 v[78:81], v[162:165], v[196:199], v[78:81]
	v_mfma_f32_16x16x32_bf16 v[74:77], v[174:177], v[190:193], v[74:77]
	v_mfma_f32_16x16x32_bf16 v[74:77], v[178:181], v[196:199], v[74:77]
	v_mfma_f32_16x16x32_bf16 v[70:73], v[182:185], v[190:193], v[70:73]
	v_mfma_f32_16x16x32_bf16 v[70:73], v[186:189], v[196:199], v[70:73]
	v_mfma_f32_16x16x32_bf16 v[54:57], v[182:185], v[200:203], v[54:57]
	v_mfma_f32_16x16x32_bf16 v[54:57], v[186:189], v[204:207], v[54:57]
	v_mfma_f32_16x16x32_bf16 v[58:61], v[174:177], v[200:203], v[58:61]
	v_mfma_f32_16x16x32_bf16 v[58:61], v[178:181], v[204:207], v[58:61]
	v_mfma_f32_16x16x32_bf16 v[62:65], v[158:161], v[200:203], v[62:65]
	v_mfma_f32_16x16x32_bf16 v[62:65], v[162:165], v[204:207], v[62:65]
	v_mfma_f32_16x16x32_bf16 v[66:69], v[150:153], v[200:203], v[66:69]
	v_mfma_f32_16x16x32_bf16 v[66:69], v[154:157], v[204:207], v[66:69]
	v_mfma_f32_16x16x32_bf16 v[42:45], v[150:153], v[208:211], v[42:45]
	v_mfma_f32_16x16x32_bf16 v[42:45], v[154:157], v[212:215], v[42:45]
	v_mfma_f32_16x16x32_bf16 v[34:37], v[158:161], v[208:211], v[34:37]
	v_mfma_f32_16x16x32_bf16 v[34:37], v[162:165], v[212:215], v[34:37]
	v_mfma_f32_16x16x32_bf16 v[26:29], v[174:177], v[208:211], v[26:29]
	v_mfma_f32_16x16x32_bf16 v[26:29], v[178:181], v[212:215], v[26:29]
	v_mfma_f32_16x16x32_bf16 v[22:25], v[182:185], v[208:211], v[22:25]
	v_mfma_f32_16x16x32_bf16 v[22:25], v[186:189], v[212:215], v[22:25]
	v_mfma_f32_16x16x32_bf16 v[4:7], v[182:185], v[220:223], v[6:9]
	v_mfma_f32_16x16x32_bf16 v[4:7], v[186:189], v[224:227], v[4:7]
	v_mfma_f32_16x16x32_bf16 v[10:13], v[174:177], v[220:223], v[10:13]
	v_mfma_f32_16x16x32_bf16 v[10:13], v[178:181], v[224:227], v[10:13]
	v_mfma_f32_16x16x32_bf16 v[14:17], v[158:161], v[220:223], v[14:17]
	v_mfma_f32_16x16x32_bf16 v[14:17], v[162:165], v[224:227], v[14:17]
	v_mfma_f32_16x16x32_bf16 v[18:21], v[150:153], v[220:223], v[18:21]
	v_mfma_f32_16x16x32_bf16 v[18:21], v[154:157], v[224:227], v[18:21]
	s_setprio 0
	s_add_i32 s0, 0, 0x18000
	v_add_u32_e32 v3, s0, v167
	s_add_i32 s1, 0, 0x1c000
	ds_read_b128 v[150:153], v3
	ds_read_b128 v[154:157], v3 offset:1024
	ds_read_b128 v[158:161], v3 offset:2048
	ds_read_b128 v[162:165], v3 offset:3072
	v_add_u32_e32 v3, s1, v167
	ds_read_b128 v[174:177], v3
	ds_read_b128 v[178:181], v3 offset:1024
	ds_read_b128 v[182:185], v3 offset:2048
	ds_read_b128 v[186:189], v3 offset:3072
	ds_read_b128 v[190:193], v171 offset:32768
	ds_read_b128 v[196:199], v171 offset:33792
	ds_read_b128 v[200:203], v171 offset:34816
	ds_read_b128 v[204:207], v171 offset:35840
	ds_read_b128 v[208:211], v171 offset:36864
	ds_read_b128 v[212:215], v171 offset:37888
	ds_read_b128 v[220:223], v171 offset:38912
	ds_read_b128 v[224:227], v171 offset:39936
	s_add_u32 vcc_lo, s92, 0x100000
	s_addc_u32 vcc_hi, s93, 0
	s_mov_b32 m0, s27
	s_nop 0
	global_load_lds_dwordx4 v134, s[92:93]
	s_add_i32 m0, s27, 0x2000
	s_nop 0
	global_load_lds_dwordx4 v138, s[92:93]
	s_add_i32 m0, s27, 0x4000
	s_nop 0
	global_load_lds_dwordx4 v134, vcc
	s_add_i32 m0, s27, 0x6000
	s_nop 0
	global_load_lds_dwordx4 v138, vcc
	s_sleep 2
	s_waitcnt lgkmcnt(0)
	s_waitcnt vmcnt(8)
	s_barrier
; #define PG8_STAGE(bufoff, gbase, voff) do { _Pragma("unroll") for (int _i = 0; _i < 2; ++_i) \
;         __builtin_amdgcn_global_load_lds((const unsigned*)((const char*)(gbase) + (voff)[_i]), (PG8_LAS unsigned*)(lds + (bufoff) + ldsw + _i * 8192), 16, 0, 0); } while (0)
; #define PG8_LDA(dst, b, h) do { _Pragma("unroll") for (int m = 0; m < 4; ++m) _Pragma("unroll") for (int k = 0; k < 2; ++k) dst[m][k] = *(const PG8_LAS bf16x8*)(lds + PG8_SA(b, h) + aoff + m * 2048 + k * 1024); } while (0)
; #define PG8_MMA(ai, bj, At, Bt) do { __builtin_amdgcn_s_setprio(1); _Pragma("unroll") for (int m = 0; m < 4; ++m) _Pragma("unroll") for (int n = 0; n < 2; ++n) _Pragma("unroll") for (int k = 0; k < 2; ++k) \
;         acc[ai][bj][m][n] = __builtin_amdgcn_mfma_f32_16x16x32_bf16(Bt[n][k], At[m][k], acc[ai][bj][m][n], 0, 0, 0); __builtin_amdgcn_s_setprio(0); } while (0)
; #define PG8_WAIT_V(n) asm volatile("s_waitcnt vmcnt(" #n ")" ::: "memory")
; #define PG8_WAIT_L(n) asm volatile("s_waitcnt lgkmcnt(" #n ")" ::: "memory")
; #define PG8_BAR __builtin_amdgcn_s_barrier()
; #define PG8_SCHED __builtin_amdgcn_sched_barrier(0)
; template <class Epi, class Sched, bool ALIGN_EPI = false, bool SP2 = false>
; __device__ __forceinline__ void gemm_phase(PG8_LAS unsigned char* lds, const Gemm g, const Sched& S, const Epi& E) {
;     ...
;         for (int t = 0; t < nt; t += 2) {
;             const bool last = (t == nt - 2);
;     ...
;             PG8_WAIT_V(8); PG8_WAIT_L(0); PG8_BAR; PG8_MMA(0, 0, At, B0); PG8_MMA(0, 1, At, B1); PG8_BAR; PG8_SCHED;
;             PG8_LDA(At, 1, 1); PG8_STAGE(PG8_SB(1, 0), b3, voffB); PG8_STAGE(PG8_SB(1, 1), b3 + hstep, voffB); PG8_STAGE(PG8_SA(1, 0), a3, voffA);
;             PG8_WAIT_V(8); PG8_WAIT_L(0); PG8_BAR; PG8_MMA(1, 0, At, B0); PG8_MMA(1, 1, At, B1); PG8_BAR; PG8_SCHED;
	s_setprio 2
	.p2align 3
	v_mfma_f32_16x16x32_bf16 v[38:41], v[150:153], v[190:193], v[38:41]
	v_mfma_f32_16x16x32_bf16 v[38:41], v[154:157], v[196:199], v[38:41]
	v_mfma_f32_16x16x32_bf16 v[30:33], v[158:161], v[190:193], v[30:33]
	v_mfma_f32_16x16x32_bf16 v[30:33], v[162:165], v[196:199], v[30:33]
	v_mfma_f32_16x16x32_bf16 v[50:53], v[174:177], v[190:193], v[50:53]
	v_mfma_f32_16x16x32_bf16 v[50:53], v[178:181], v[196:199], v[50:53]
	v_mfma_f32_16x16x32_bf16 v[46:49], v[182:185], v[190:193], v[46:49]
	v_mfma_f32_16x16x32_bf16 v[46:49], v[186:189], v[196:199], v[46:49]
	v_mfma_f32_16x16x32_bf16 v[118:121], v[182:185], v[200:203], v[118:121]
	v_mfma_f32_16x16x32_bf16 v[118:121], v[186:189], v[204:207], v[118:121]
	v_mfma_f32_16x16x32_bf16 v[122:125], v[174:177], v[200:203], v[122:125]
	v_mfma_f32_16x16x32_bf16 v[122:125], v[178:181], v[204:207], v[122:125]
	v_mfma_f32_16x16x32_bf16 v[126:129], v[158:161], v[200:203], v[126:129]
	v_mfma_f32_16x16x32_bf16 v[126:129], v[162:165], v[204:207], v[126:129]
	v_mfma_f32_16x16x32_bf16 v[130:133], v[150:153], v[200:203], v[130:133]
	v_mfma_f32_16x16x32_bf16 v[130:133], v[154:157], v[204:207], v[130:133]
	v_mfma_f32_16x16x32_bf16 v[114:117], v[150:153], v[208:211], v[114:117]
	v_mfma_f32_16x16x32_bf16 v[114:117], v[154:157], v[212:215], v[114:117]
	v_mfma_f32_16x16x32_bf16 v[110:113], v[158:161], v[208:211], v[110:113]
	v_mfma_f32_16x16x32_bf16 v[110:113], v[162:165], v[212:215], v[110:113]
	v_mfma_f32_16x16x32_bf16 v[106:109], v[174:177], v[208:211], v[106:109]
	v_mfma_f32_16x16x32_bf16 v[106:109], v[178:181], v[212:215], v[106:109]
	v_mfma_f32_16x16x32_bf16 v[102:105], v[182:185], v[208:211], v[102:105]
	v_mfma_f32_16x16x32_bf16 v[102:105], v[186:189], v[212:215], v[102:105]
	v_mfma_f32_16x16x32_bf16 v[86:89], v[182:185], v[220:223], v[86:89]
	v_mfma_f32_16x16x32_bf16 v[86:89], v[186:189], v[224:227], v[86:89]
	v_mfma_f32_16x16x32_bf16 v[90:93], v[174:177], v[220:223], v[90:93]
	v_mfma_f32_16x16x32_bf16 v[90:93], v[178:181], v[224:227], v[90:93]
	v_mfma_f32_16x16x32_bf16 v[94:97], v[158:161], v[220:223], v[94:97]
	v_mfma_f32_16x16x32_bf16 v[94:97], v[162:165], v[224:227], v[94:97]
	v_mfma_f32_16x16x32_bf16 v[98:101], v[150:153], v[220:223], v[98:101]
	v_mfma_f32_16x16x32_bf16 v[98:101], v[154:157], v[224:227], v[98:101]
	s_setprio 0
	ds_read_b128 v[190:193], v171 offset:49152
	ds_read_b128 v[196:199], v171 offset:50176
	ds_read_b128 v[200:203], v171 offset:51200
	ds_read_b128 v[204:207], v171 offset:52224
	ds_read_b128 v[208:211], v171 offset:53248
	ds_read_b128 v[212:215], v171 offset:54272
	ds_read_b128 v[220:223], v171 offset:55296
	ds_read_b128 v[224:227], v171 offset:56320
	s_add_u32 s0, s90, 0x80
	s_addc_u32 s1, s91, 0
	s_add_u32 vcc_lo, s0, 0x100000
	s_addc_u32 vcc_hi, s1, 0
	s_add_i32 m0, s27, 0x18000
	s_nop 0
	global_load_lds_dwordx4 v136, s[0:1]
	s_add_i32 m0, s27, 0x1a000
	s_nop 0
	global_load_lds_dwordx4 v140, s[0:1]
	s_add_i32 m0, s27, 0x1c000
	s_nop 0
	global_load_lds_dwordx4 v136, vcc
	s_add_i32 m0, s27, 0x1e000
	s_nop 0
	global_load_lds_dwordx4 v140, vcc
	s_sleep 2
	s_waitcnt lgkmcnt(0)
	s_waitcnt vmcnt(6)
	s_barrier
	s_setprio 2
	.p2align 3
	v_mfma_f32_16x16x32_bf16 v[70:73], v[182:185], v[190:193], v[70:73]
	v_mfma_f32_16x16x32_bf16 v[70:73], v[186:189], v[196:199], v[70:73]
	v_mfma_f32_16x16x32_bf16 v[74:77], v[174:177], v[190:193], v[74:77]
	v_mfma_f32_16x16x32_bf16 v[74:77], v[178:181], v[196:199], v[74:77]
	v_mfma_f32_16x16x32_bf16 v[78:81], v[158:161], v[190:193], v[78:81]
	v_mfma_f32_16x16x32_bf16 v[78:81], v[162:165], v[196:199], v[78:81]
	v_mfma_f32_16x16x32_bf16 v[82:85], v[150:153], v[190:193], v[82:85]
	v_mfma_f32_16x16x32_bf16 v[82:85], v[154:157], v[196:199], v[82:85]
	v_mfma_f32_16x16x32_bf16 v[66:69], v[150:153], v[200:203], v[66:69]
	v_mfma_f32_16x16x32_bf16 v[66:69], v[154:157], v[204:207], v[66:69]
	v_mfma_f32_16x16x32_bf16 v[62:65], v[158:161], v[200:203], v[62:65]
	v_mfma_f32_16x16x32_bf16 v[62:65], v[162:165], v[204:207], v[62:65]
	v_mfma_f32_16x16x32_bf16 v[58:61], v[174:177], v[200:203], v[58:61]
	v_mfma_f32_16x16x32_bf16 v[58:61], v[178:181], v[204:207], v[58:61]
	v_mfma_f32_16x16x32_bf16 v[54:57], v[182:185], v[200:203], v[54:57]
	v_mfma_f32_16x16x32_bf16 v[54:57], v[186:189], v[204:207], v[54:57]
	v_mfma_f32_16x16x32_bf16 v[22:25], v[182:185], v[208:211], v[22:25]
	v_mfma_f32_16x16x32_bf16 v[22:25], v[186:189], v[212:215], v[22:25]
	v_mfma_f32_16x16x32_bf16 v[26:29], v[174:177], v[208:211], v[26:29]
	v_mfma_f32_16x16x32_bf16 v[26:29], v[178:181], v[212:215], v[26:29]
	v_mfma_f32_16x16x32_bf16 v[34:37], v[158:161], v[208:211], v[34:37]
	v_mfma_f32_16x16x32_bf16 v[34:37], v[162:165], v[212:215], v[34:37]
	v_mfma_f32_16x16x32_bf16 v[42:45], v[150:153], v[208:211], v[42:45]
	v_mfma_f32_16x16x32_bf16 v[42:45], v[154:157], v[212:215], v[42:45]
	v_mfma_f32_16x16x32_bf16 v[18:21], v[150:153], v[220:223], v[18:21]
	v_mfma_f32_16x16x32_bf16 v[18:21], v[154:157], v[224:227], v[18:21]
	v_mfma_f32_16x16x32_bf16 v[14:17], v[158:161], v[220:223], v[14:17]
	v_mfma_f32_16x16x32_bf16 v[14:17], v[162:165], v[224:227], v[14:17]
	v_mfma_f32_16x16x32_bf16 v[8:11], v[174:177], v[220:223], v[10:13]
	v_mfma_f32_16x16x32_bf16 v[10:13], v[178:181], v[224:227], v[8:11]
	v_mfma_f32_16x16x32_bf16 v[4:7], v[182:185], v[220:223], v[4:7]
	v_mfma_f32_16x16x32_bf16 v[6:9], v[186:189], v[224:227], v[4:7]
	s_setprio 0
	s_add_i32 s23, s23, 2
	s_add_u32 s88, s88, 0x100
	s_addc_u32 s89, s89, 0
	s_add_u32 s9, s9, 0x100
	s_addc_u32 s21, s21, 0
	s_cmp_gt_u32 s23, 61
	s_cbranch_scc0 .Lip_h1

; #define PG8_STAGE(bufoff, gbase, voff) do { _Pragma("unroll") for (int _i = 0; _i < 2; ++_i) \
;         __builtin_amdgcn_global_load_lds((const unsigned*)((const char*)(gbase) + (voff)[_i]), (PG8_LAS unsigned*)(lds + (bufoff) + ldsw + _i * 8192), 16, 0, 0); } while (0)
; #define PG8_LDA(dst, b, h) do { _Pragma("unroll") for (int m = 0; m < 4; ++m) _Pragma("unroll") for (int k = 0; k < 2; ++k) dst[m][k] = *(const PG8_LAS bf16x8*)(lds + PG8_SA(b, h) + aoff + m * 2048 + k * 1024); } while (0)
; #define PG8_LDB(dst, b, h) do { _Pragma("unroll") for (int n = 0; n < 2; ++n) _Pragma("unroll") for (int k = 0; k < 2; ++k) dst[n][k] = *(const PG8_LAS bf16x8*)(lds + PG8_SB(b, h) + boff + n * 2048 + k * 1024); } while (0)
; #define PG8_MMA(ai, bj, At, Bt) do { __builtin_amdgcn_s_setprio(1); _Pragma("unroll") for (int m = 0; m < 4; ++m) _Pragma("unroll") for (int n = 0; n < 2; ++n) _Pragma("unroll") for (int k = 0; k < 2; ++k) \
;         acc[ai][bj][m][n] = __builtin_amdgcn_mfma_f32_16x16x32_bf16(Bt[n][k], At[m][k], acc[ai][bj][m][n], 0, 0, 0); __builtin_amdgcn_s_setprio(0); } while (0)
; #define PG8_WAIT_V(n) asm volatile("s_waitcnt vmcnt(" #n ")" ::: "memory")
; #define PG8_WAIT_L(n) asm volatile("s_waitcnt lgkmcnt(" #n ")" ::: "memory")
; #define PG8_BAR __builtin_amdgcn_s_barrier()
; #define PG8_SCHED __builtin_amdgcn_sched_barrier(0)
; template <class Epi, class Sched, bool ALIGN_EPI = false, bool SP2 = false>
; __device__ __forceinline__ void gemm_phase(PG8_LAS unsigned char* lds, const Gemm g, const Sched& S, const Epi& E) {
;     ...
;             PG8_LDB(B0, 0, 0); PG8_LDB(B1, 0, 1); PG8_SCHED; PG8_LDA(At, 0, 0); PG8_STAGE(PG8_SA(1, 1), a1 + hstep, voffA);
;             PG8_WAIT_V(8); PG8_WAIT_L(0); PG8_BAR; PG8_MMA(0, 0, At, B0); PG8_MMA(0, 1, At, B1); PG8_BAR; PG8_SCHED;
;             PG8_LDA(At, 0, 1); PG8_STAGE(PG8_SB(0, 0), b2, voffB); PG8_STAGE(PG8_SB(0, 1), b2 + hstep, voffB); PG8_STAGE(PG8_SA(0, 0), a2, voffA);
;             PG8_WAIT_V(8); PG8_WAIT_L(0); PG8_BAR; PG8_MMA(1, 0, At, B0); PG8_MMA(1, 1, At, B1); PG8_BAR; PG8_SCHED;
.LBB0_1251:
	ds_read_b128 v[130:133], v177
	ds_read_b128 v[134:137], v177 offset:1024
	ds_read_b128 v[138:141], v177 offset:2048
	ds_read_b128 v[142:145], v177 offset:3072
	ds_read_b128 v[162:165], v178
	ds_read_b128 v[180:183], v178 offset:1024
	ds_read_b128 v[184:187], v178 offset:2048
	ds_read_b128 v[188:191], v178 offset:3072
	s_add_u32 s40, s36, 0xfff00080
	s_addc_u32 s41, s37, -1
	s_cmp_eq_u32 s58, 60
	s_cselect_b32 s43, s15, s41
	s_cselect_b32 s42, s17, s40
	s_cselect_b32 s41, s54, s57
	s_cselect_b32 s40, s55, s56
	ds_read_b128 v[196:199], v179
	ds_read_b128 v[200:203], v179 offset:1024
	ds_read_b128 v[204:207], v179 offset:2048
	ds_read_b128 v[208:211], v179 offset:3072
	ds_read_b128 v[212:215], v179 offset:4096
	ds_read_b128 v[220:223], v179 offset:5120
	ds_read_b128 v[224:227], v179 offset:6144
	ds_read_b128 v[228:231], v179 offset:7168
	s_add_i32 m0, s24, 0xc000
	s_nop 0
	global_load_lds_dwordx4 v146, s[36:37]
	s_add_i32 m0, s24, 0xe000
	s_nop 0
	global_load_lds_dwordx4 v150, s[36:37]
	s_waitcnt lgkmcnt(0)
	s_setprio 1
	.p2align 3
	v_mfma_f32_16x16x32_bf16 v[126:129], v[130:133], v[196:199], v[126:129]
	v_mfma_f32_16x16x32_bf16 v[126:129], v[134:137], v[200:203], v[126:129]
	v_mfma_f32_16x16x32_bf16 v[122:125], v[138:141], v[196:199], v[122:125]
	v_mfma_f32_16x16x32_bf16 v[122:125], v[142:145], v[200:203], v[122:125]
	v_mfma_f32_16x16x32_bf16 v[118:121], v[162:165], v[196:199], v[118:121]
	v_mfma_f32_16x16x32_bf16 v[118:121], v[180:183], v[200:203], v[118:121]
	v_mfma_f32_16x16x32_bf16 v[114:117], v[184:187], v[196:199], v[114:117]
	v_mfma_f32_16x16x32_bf16 v[114:117], v[188:191], v[200:203], v[114:117]
	v_mfma_f32_16x16x32_bf16 v[98:101], v[184:187], v[204:207], v[98:101]
	v_mfma_f32_16x16x32_bf16 v[98:101], v[188:191], v[208:211], v[98:101]
	v_mfma_f32_16x16x32_bf16 v[102:105], v[162:165], v[204:207], v[102:105]
	v_mfma_f32_16x16x32_bf16 v[102:105], v[180:183], v[208:211], v[102:105]
	v_mfma_f32_16x16x32_bf16 v[106:109], v[138:141], v[204:207], v[106:109]
	v_mfma_f32_16x16x32_bf16 v[106:109], v[142:145], v[208:211], v[106:109]
	v_mfma_f32_16x16x32_bf16 v[110:113], v[130:133], v[204:207], v[110:113]
	v_mfma_f32_16x16x32_bf16 v[110:113], v[134:137], v[208:211], v[110:113]
	v_mfma_f32_16x16x32_bf16 v[94:97], v[130:133], v[212:215], v[94:97]
	v_mfma_f32_16x16x32_bf16 v[94:97], v[134:137], v[220:223], v[94:97]
	v_mfma_f32_16x16x32_bf16 v[90:93], v[138:141], v[212:215], v[90:93]
	v_mfma_f32_16x16x32_bf16 v[90:93], v[142:145], v[220:223], v[90:93]
	v_mfma_f32_16x16x32_bf16 v[86:89], v[162:165], v[212:215], v[86:89]
	v_mfma_f32_16x16x32_bf16 v[86:89], v[180:183], v[220:223], v[86:89]
	v_mfma_f32_16x16x32_bf16 v[82:85], v[184:187], v[212:215], v[82:85]
	v_mfma_f32_16x16x32_bf16 v[82:85], v[188:191], v[220:223], v[82:85]
	v_mfma_f32_16x16x32_bf16 v[66:69], v[184:187], v[224:227], v[66:69]
	v_mfma_f32_16x16x32_bf16 v[66:69], v[188:191], v[228:231], v[66:69]
	v_mfma_f32_16x16x32_bf16 v[70:73], v[162:165], v[224:227], v[70:73]
	v_mfma_f32_16x16x32_bf16 v[70:73], v[180:183], v[228:231], v[70:73]
	v_mfma_f32_16x16x32_bf16 v[74:77], v[138:141], v[224:227], v[74:77]
	v_mfma_f32_16x16x32_bf16 v[74:77], v[142:145], v[228:231], v[74:77]
	v_mfma_f32_16x16x32_bf16 v[78:81], v[130:133], v[224:227], v[78:81]
	v_mfma_f32_16x16x32_bf16 v[78:81], v[134:137], v[228:231], v[78:81]
	s_setprio 0
	s_waitcnt vmcnt(8)
	s_barrier
	ds_read_b128 v[196:199], v179 offset:16384
	ds_read_b128 v[200:203], v179 offset:17408
	ds_read_b128 v[204:207], v179 offset:18432
	ds_read_b128 v[208:211], v179 offset:19456
	ds_read_b128 v[212:215], v179 offset:20480
	ds_read_b128 v[220:223], v179 offset:21504
	ds_read_b128 v[224:227], v179 offset:22528
	ds_read_b128 v[228:231], v179 offset:23552
	s_add_u32 vcc_lo, s40, 0x100000
	s_addc_u32 vcc_hi, s41, 0
	s_add_i32 m0, s24, 0x10000
	s_nop 0
	global_load_lds_dwordx4 v148, s[40:41]
	s_add_i32 m0, s24, 0x12000
	s_nop 0
	global_load_lds_dwordx4 v152, s[40:41]
	s_add_i32 m0, s24, 0x14000
	s_nop 0
	global_load_lds_dwordx4 v148, vcc
	s_add_i32 m0, s24, 0x16000
	s_nop 0
	global_load_lds_dwordx4 v152, vcc
	s_mov_b32 m0, s24
	s_nop 0
	global_load_lds_dwordx4 v146, s[42:43]
	s_add_i32 m0, s24, 0x2000
	s_nop 0
	global_load_lds_dwordx4 v150, s[42:43]
	s_waitcnt lgkmcnt(0)
	s_setprio 1
	.p2align 3
	v_mfma_f32_16x16x32_bf16 v[62:65], v[130:133], v[196:199], v[62:65]
	v_mfma_f32_16x16x32_bf16 v[62:65], v[134:137], v[200:203], v[62:65]
	v_mfma_f32_16x16x32_bf16 v[58:61], v[138:141], v[196:199], v[58:61]
	v_mfma_f32_16x16x32_bf16 v[58:61], v[142:145], v[200:203], v[58:61]
	v_mfma_f32_16x16x32_bf16 v[54:57], v[162:165], v[196:199], v[54:57]
	v_mfma_f32_16x16x32_bf16 v[54:57], v[180:183], v[200:203], v[54:57]
	v_mfma_f32_16x16x32_bf16 v[50:53], v[184:187], v[196:199], v[50:53]
	v_mfma_f32_16x16x32_bf16 v[50:53], v[188:191], v[200:203], v[50:53]
	v_mfma_f32_16x16x32_bf16 v[34:37], v[184:187], v[204:207], v[34:37]
	v_mfma_f32_16x16x32_bf16 v[34:37], v[188:191], v[208:211], v[34:37]
	v_mfma_f32_16x16x32_bf16 v[38:41], v[162:165], v[204:207], v[38:41]
	v_mfma_f32_16x16x32_bf16 v[38:41], v[180:183], v[208:211], v[38:41]
	v_mfma_f32_16x16x32_bf16 v[42:45], v[138:141], v[204:207], v[42:45]
	v_mfma_f32_16x16x32_bf16 v[42:45], v[142:145], v[208:211], v[42:45]
	v_mfma_f32_16x16x32_bf16 v[46:49], v[130:133], v[204:207], v[46:49]
	v_mfma_f32_16x16x32_bf16 v[46:49], v[134:137], v[208:211], v[46:49]
	v_mfma_f32_16x16x32_bf16 v[30:33], v[130:133], v[212:215], v[30:33]
	v_mfma_f32_16x16x32_bf16 v[30:33], v[134:137], v[220:223], v[30:33]
	v_mfma_f32_16x16x32_bf16 v[26:29], v[138:141], v[212:215], v[26:29]
	v_mfma_f32_16x16x32_bf16 v[26:29], v[142:145], v[220:223], v[26:29]
	v_mfma_f32_16x16x32_bf16 v[22:25], v[162:165], v[212:215], v[22:25]
	v_mfma_f32_16x16x32_bf16 v[22:25], v[180:183], v[220:223], v[22:25]
	v_mfma_f32_16x16x32_bf16 v[18:21], v[184:187], v[212:215], v[18:21]
	v_mfma_f32_16x16x32_bf16 v[18:21], v[188:191], v[220:223], v[18:21]
	v_mfma_f32_16x16x32_bf16 v[2:5], v[184:187], v[224:227], v[2:5]
	v_mfma_f32_16x16x32_bf16 v[2:5], v[188:191], v[228:231], v[2:5]
	v_mfma_f32_16x16x32_bf16 v[6:9], v[162:165], v[224:227], v[6:9]
	v_mfma_f32_16x16x32_bf16 v[6:9], v[180:183], v[228:231], v[6:9]
	v_mfma_f32_16x16x32_bf16 v[10:13], v[138:141], v[224:227], v[10:13]
	v_mfma_f32_16x16x32_bf16 v[10:13], v[142:145], v[228:231], v[10:13]
	v_mfma_f32_16x16x32_bf16 v[14:17], v[130:133], v[224:227], v[14:17]
	v_mfma_f32_16x16x32_bf16 v[14:17], v[134:137], v[228:231], v[14:17]
	s_setprio 0
	s_waitcnt vmcnt(8)
	s_barrier
; #define PG8_STAGE(bufoff, gbase, voff) do { _Pragma("unroll") for (int _i = 0; _i < 2; ++_i) \
;         __builtin_amdgcn_global_load_lds((const unsigned*)((const char*)(gbase) + (voff)[_i]), (PG8_LAS unsigned*)(lds + (bufoff) + ldsw + _i * 8192), 16, 0, 0); } while (0)
; #define PG8_LDA(dst, b, h) do { _Pragma("unroll") for (int m = 0; m < 4; ++m) _Pragma("unroll") for (int k = 0; k < 2; ++k) dst[m][k] = *(const PG8_LAS bf16x8*)(lds + PG8_SA(b, h) + aoff + m * 2048 + k * 1024); } while (0)
; #define PG8_LDB(dst, b, h) do { _Pragma("unroll") for (int n = 0; n < 2; ++n) _Pragma("unroll") for (int k = 0; k < 2; ++k) dst[n][k] = *(const PG8_LAS bf16x8*)(lds + PG8_SB(b, h) + boff + n * 2048 + k * 1024); } while (0)
; #define PG8_MMA(ai, bj, At, Bt) do { __builtin_amdgcn_s_setprio(1); _Pragma("unroll") for (int m = 0; m < 4; ++m) _Pragma("unroll") for (int n = 0; n < 2; ++n) _Pragma("unroll") for (int k = 0; k < 2; ++k) \
;         acc[ai][bj][m][n] = __builtin_amdgcn_mfma_f32_16x16x32_bf16(Bt[n][k], At[m][k], acc[ai][bj][m][n], 0, 0, 0); __builtin_amdgcn_s_setprio(0); } while (0)
; #define PG8_WAIT_V(n) asm volatile("s_waitcnt vmcnt(" #n ")" ::: "memory")
; #define PG8_WAIT_L(n) asm volatile("s_waitcnt lgkmcnt(" #n ")" ::: "memory")
; #define PG8_BAR __builtin_amdgcn_s_barrier()
; #define PG8_SCHED __builtin_amdgcn_sched_barrier(0)
; template <class Epi, class Sched, bool ALIGN_EPI = false, bool SP2 = false>
; __device__ __forceinline__ void gemm_phase(PG8_LAS unsigned char* lds, const Gemm g, const Sched& S, const Epi& E) {
;     ...
;         for (int t = 0; t < nt; t += 2) {
;             const bool last = (t == nt - 2);
;     ...
;             PG8_LDB(B0, 1, 0); PG8_LDB(B1, 1, 1); PG8_SCHED; PG8_LDA(At, 1, 0); PG8_STAGE(PG8_SA(0, 1), a2 + hstep, voffA);
;             PG8_WAIT_V(8); PG8_WAIT_L(0); PG8_BAR; PG8_MMA(0, 0, At, B0); PG8_MMA(0, 1, At, B1); PG8_BAR; PG8_SCHED;
;             PG8_LDA(At, 1, 1); PG8_STAGE(PG8_SB(1, 0), b3, voffB); PG8_STAGE(PG8_SB(1, 1), b3 + hstep, voffB); PG8_STAGE(PG8_SA(1, 0), a3, voffA);
;             PG8_WAIT_V(8); PG8_WAIT_L(0); PG8_BAR; PG8_MMA(1, 0, At, B0); PG8_MMA(1, 1, At, B1); PG8_BAR; PG8_SCHED;
	s_add_i32 s59, 0, 0x18000
	s_add_i32 s60, 0, 0x1c000
	v_add_u32_e32 v142, s59, v166
	v_add_u32_e32 v188, s60, v166
	ds_read_b128 v[130:133], v142
	ds_read_b128 v[134:137], v142 offset:1024
	ds_read_b128 v[138:141], v142 offset:2048
	ds_read_b128 v[142:145], v142 offset:3072
	ds_read_b128 v[162:165], v188
	ds_read_b128 v[180:183], v188 offset:1024
	ds_read_b128 v[184:187], v188 offset:2048
	ds_read_b128 v[188:191], v188 offset:3072
	ds_read_b128 v[196:199], v179 offset:32768
	ds_read_b128 v[200:203], v179 offset:33792
	ds_read_b128 v[204:207], v179 offset:34816
	ds_read_b128 v[208:211], v179 offset:35840
	ds_read_b128 v[212:215], v179 offset:36864
	ds_read_b128 v[220:223], v179 offset:37888
	ds_read_b128 v[224:227], v179 offset:38912
	ds_read_b128 v[228:231], v179 offset:39936
	s_add_u32 vcc_lo, s42, 0x100000
	s_addc_u32 vcc_hi, s43, 0
	s_add_i32 m0, s24, 0x4000
	s_nop 0
	global_load_lds_dwordx4 v146, vcc
	s_add_i32 m0, s24, 0x6000
	s_nop 0
	global_load_lds_dwordx4 v150, vcc
	s_waitcnt lgkmcnt(0)
	s_setprio 1
	.p2align 3
	v_mfma_f32_16x16x32_bf16 v[126:129], v[130:133], v[196:199], v[126:129]
	v_mfma_f32_16x16x32_bf16 v[126:129], v[134:137], v[200:203], v[126:129]
	v_mfma_f32_16x16x32_bf16 v[122:125], v[138:141], v[196:199], v[122:125]
	v_mfma_f32_16x16x32_bf16 v[122:125], v[142:145], v[200:203], v[122:125]
	v_mfma_f32_16x16x32_bf16 v[118:121], v[162:165], v[196:199], v[118:121]
	v_mfma_f32_16x16x32_bf16 v[118:121], v[180:183], v[200:203], v[118:121]
	v_mfma_f32_16x16x32_bf16 v[114:117], v[184:187], v[196:199], v[114:117]
	v_mfma_f32_16x16x32_bf16 v[114:117], v[188:191], v[200:203], v[114:117]
	v_mfma_f32_16x16x32_bf16 v[98:101], v[184:187], v[204:207], v[98:101]
	v_mfma_f32_16x16x32_bf16 v[98:101], v[188:191], v[208:211], v[98:101]
	v_mfma_f32_16x16x32_bf16 v[102:105], v[162:165], v[204:207], v[102:105]
	v_mfma_f32_16x16x32_bf16 v[102:105], v[180:183], v[208:211], v[102:105]
	v_mfma_f32_16x16x32_bf16 v[106:109], v[138:141], v[204:207], v[106:109]
	v_mfma_f32_16x16x32_bf16 v[106:109], v[142:145], v[208:211], v[106:109]
	v_mfma_f32_16x16x32_bf16 v[110:113], v[130:133], v[204:207], v[110:113]
	v_mfma_f32_16x16x32_bf16 v[110:113], v[134:137], v[208:211], v[110:113]
	v_mfma_f32_16x16x32_bf16 v[94:97], v[130:133], v[212:215], v[94:97]
	v_mfma_f32_16x16x32_bf16 v[94:97], v[134:137], v[220:223], v[94:97]
	v_mfma_f32_16x16x32_bf16 v[90:93], v[138:141], v[212:215], v[90:93]
	v_mfma_f32_16x16x32_bf16 v[90:93], v[142:145], v[220:223], v[90:93]
	v_mfma_f32_16x16x32_bf16 v[86:89], v[162:165], v[212:215], v[86:89]
	v_mfma_f32_16x16x32_bf16 v[86:89], v[180:183], v[220:223], v[86:89]
	v_mfma_f32_16x16x32_bf16 v[82:85], v[184:187], v[212:215], v[82:85]
	v_mfma_f32_16x16x32_bf16 v[82:85], v[188:191], v[220:223], v[82:85]
	v_mfma_f32_16x16x32_bf16 v[66:69], v[184:187], v[224:227], v[66:69]
	v_mfma_f32_16x16x32_bf16 v[66:69], v[188:191], v[228:231], v[66:69]
	v_mfma_f32_16x16x32_bf16 v[70:73], v[162:165], v[224:227], v[70:73]
	v_mfma_f32_16x16x32_bf16 v[70:73], v[180:183], v[228:231], v[70:73]
	v_mfma_f32_16x16x32_bf16 v[74:77], v[138:141], v[224:227], v[74:77]
	v_mfma_f32_16x16x32_bf16 v[74:77], v[142:145], v[228:231], v[74:77]
	v_mfma_f32_16x16x32_bf16 v[78:81], v[130:133], v[224:227], v[78:81]
	v_mfma_f32_16x16x32_bf16 v[78:81], v[134:137], v[228:231], v[78:81]
	s_setprio 0
	s_waitcnt vmcnt(8)
	s_barrier
	ds_read_b128 v[196:199], v179 offset:49152
	ds_read_b128 v[200:203], v179 offset:50176
	ds_read_b128 v[204:207], v179 offset:51200
	ds_read_b128 v[208:211], v179 offset:52224
	ds_read_b128 v[212:215], v179 offset:53248
	ds_read_b128 v[220:223], v179 offset:54272
	ds_read_b128 v[224:227], v179 offset:55296
	ds_read_b128 v[228:231], v179 offset:56320
	s_add_u32 s60, s40, 0x80
	s_addc_u32 s61, s41, 0
	s_add_u32 vcc_lo, s60, 0x100000
	s_addc_u32 vcc_hi, s61, 0
	s_add_i32 m0, s24, 0x18000
	s_nop 0
	global_load_lds_dwordx4 v148, s[60:61]
	s_add_i32 m0, s24, 0x1a000
	s_nop 0
	global_load_lds_dwordx4 v152, s[60:61]
	s_add_i32 m0, s24, 0x1c000
	s_nop 0
	global_load_lds_dwordx4 v148, vcc
	s_add_i32 m0, s24, 0x1e000
	s_nop 0
	global_load_lds_dwordx4 v152, vcc
	s_add_u32 s60, s42, 0x80
	s_addc_u32 s61, s43, 0
	s_add_i32 m0, s24, 0x8000
	s_nop 0
	global_load_lds_dwordx4 v146, s[60:61]
	s_add_i32 m0, s24, 0xa000
	s_nop 0
	global_load_lds_dwordx4 v150, s[60:61]
	s_waitcnt lgkmcnt(0)
	s_setprio 1
	.p2align 3
	v_mfma_f32_16x16x32_bf16 v[62:65], v[130:133], v[196:199], v[62:65]
	v_mfma_f32_16x16x32_bf16 v[62:65], v[134:137], v[200:203], v[62:65]
	v_mfma_f32_16x16x32_bf16 v[58:61], v[138:141], v[196:199], v[58:61]
	v_mfma_f32_16x16x32_bf16 v[58:61], v[142:145], v[200:203], v[58:61]
	v_mfma_f32_16x16x32_bf16 v[54:57], v[162:165], v[196:199], v[54:57]
	v_mfma_f32_16x16x32_bf16 v[54:57], v[180:183], v[200:203], v[54:57]
	v_mfma_f32_16x16x32_bf16 v[50:53], v[184:187], v[196:199], v[50:53]
	v_mfma_f32_16x16x32_bf16 v[50:53], v[188:191], v[200:203], v[50:53]
	v_mfma_f32_16x16x32_bf16 v[34:37], v[184:187], v[204:207], v[34:37]
	v_mfma_f32_16x16x32_bf16 v[34:37], v[188:191], v[208:211], v[34:37]
	v_mfma_f32_16x16x32_bf16 v[38:41], v[162:165], v[204:207], v[38:41]
	v_mfma_f32_16x16x32_bf16 v[38:41], v[180:183], v[208:211], v[38:41]
	v_mfma_f32_16x16x32_bf16 v[42:45], v[138:141], v[204:207], v[42:45]
	v_mfma_f32_16x16x32_bf16 v[42:45], v[142:145], v[208:211], v[42:45]
	v_mfma_f32_16x16x32_bf16 v[46:49], v[130:133], v[204:207], v[46:49]
	v_mfma_f32_16x16x32_bf16 v[46:49], v[134:137], v[208:211], v[46:49]
	v_mfma_f32_16x16x32_bf16 v[30:33], v[130:133], v[212:215], v[30:33]
	v_mfma_f32_16x16x32_bf16 v[30:33], v[134:137], v[220:223], v[30:33]
	v_mfma_f32_16x16x32_bf16 v[26:29], v[138:141], v[212:215], v[26:29]
	v_mfma_f32_16x16x32_bf16 v[26:29], v[142:145], v[220:223], v[26:29]
	v_mfma_f32_16x16x32_bf16 v[22:25], v[162:165], v[212:215], v[22:25]
	v_mfma_f32_16x16x32_bf16 v[22:25], v[180:183], v[220:223], v[22:25]
	v_mfma_f32_16x16x32_bf16 v[18:21], v[184:187], v[212:215], v[18:21]
	v_mfma_f32_16x16x32_bf16 v[18:21], v[188:191], v[220:223], v[18:21]
	v_mfma_f32_16x16x32_bf16 v[2:5], v[184:187], v[224:227], v[2:5]
	v_mfma_f32_16x16x32_bf16 v[2:5], v[188:191], v[228:231], v[2:5]
	v_mfma_f32_16x16x32_bf16 v[6:9], v[162:165], v[224:227], v[6:9]
	v_mfma_f32_16x16x32_bf16 v[6:9], v[180:183], v[228:231], v[6:9]
	v_mfma_f32_16x16x32_bf16 v[10:13], v[138:141], v[224:227], v[10:13]
	v_mfma_f32_16x16x32_bf16 v[10:13], v[142:145], v[228:231], v[10:13]
	v_mfma_f32_16x16x32_bf16 v[14:17], v[130:133], v[224:227], v[14:17]
	v_mfma_f32_16x16x32_bf16 v[14:17], v[134:137], v[228:231], v[14:17]
	s_setprio 0
	s_waitcnt vmcnt(8)
	s_barrier
	s_add_i32 s58, s58, 2
	s_add_u32 s36, s36, 0x100
	s_addc_u32 s37, s37, 0
	s_add_u32 s56, s56, 0x100
	s_addc_u32 s57, s57, 0
	s_cmp_gt_u32 s58, 61
	s_cbranch_scc0 .LBB0_1251
	s_branch .Lf1_exit
; #define PG8_STAGE(bufoff, gbase, voff) do { _Pragma("unroll") for (int _i = 0; _i < 2; ++_i) \
;         __builtin_amdgcn_global_load_lds((const unsigned*)((const char*)(gbase) + (voff)[_i]), (PG8_LAS unsigned*)(lds + (bufoff) + ldsw + _i * 8192), 16, 0, 0); } while (0)
; #define PG8_LDA(dst, b, h) do { _Pragma("unroll") for (int m = 0; m < 4; ++m) _Pragma("unroll") for (int k = 0; k < 2; ++k) dst[m][k] = *(const PG8_LAS bf16x8*)(lds + PG8_SA(b, h) + aoff + m * 2048 + k * 1024); } while (0)
; #define PG8_LDB(dst, b, h) do { _Pragma("unroll") for (int n = 0; n < 2; ++n) _Pragma("unroll") for (int k = 0; k < 2; ++k) dst[n][k] = *(const PG8_LAS bf16x8*)(lds + PG8_SB(b, h) + boff + n * 2048 + k * 1024); } while (0)
; #define PG8_MMA(ai, bj, At, Bt) do { __builtin_amdgcn_s_setprio(1); _Pragma("unroll") for (int m = 0; m < 4; ++m) _Pragma("unroll") for (int n = 0; n < 2; ++n) _Pragma("unroll") for (int k = 0; k < 2; ++k) \
;         acc[ai][bj][m][n] = __builtin_amdgcn_mfma_f32_16x16x32_bf16(Bt[n][k], At[m][k], acc[ai][bj][m][n], 0, 0, 0); __builtin_amdgcn_s_setprio(0); } while (0)
; #define PG8_WAIT_V(n) asm volatile("s_waitcnt vmcnt(" #n ")" ::: "memory")
; #define PG8_WAIT_L(n) asm volatile("s_waitcnt lgkmcnt(" #n ")" ::: "memory")
; #define PG8_BAR __builtin_amdgcn_s_barrier()
; #define PG8_SCHED __builtin_amdgcn_sched_barrier(0)
; template <class Epi, class Sched, bool ALIGN_EPI = false, bool SP2 = false>
; __device__ __forceinline__ void gemm_phase(PG8_LAS unsigned char* lds, const Gemm g, const Sched& S, const Epi& E) {
;     ...
;             PG8_LDB(B0, 0, 0); PG8_LDB(B1, 0, 1); PG8_SCHED; PG8_LDA(At, 0, 0); PG8_STAGE(PG8_SA(1, 1), a1 + hstep, voffA);
;             PG8_WAIT_V(8); PG8_WAIT_L(0); PG8_BAR; PG8_MMA(0, 0, At, B0); PG8_MMA(0, 1, At, B1); PG8_BAR; PG8_SCHED;
;             PG8_LDA(At, 0, 1); PG8_STAGE(PG8_SB(0, 0), b2, voffB); PG8_STAGE(PG8_SB(0, 1), b2 + hstep, voffB); PG8_STAGE(PG8_SA(0, 0), a2, voffA);
;             PG8_WAIT_V(8); PG8_WAIT_L(0); PG8_BAR; PG8_MMA(1, 0, At, B0); PG8_MMA(1, 1, At, B1); PG8_BAR; PG8_SCHED;
.Lf1_h1:
	ds_read_b128 v[130:133], v177
	ds_read_b128 v[134:137], v177 offset:1024
	ds_read_b128 v[138:141], v177 offset:2048
	ds_read_b128 v[142:145], v177 offset:3072
	ds_read_b128 v[162:165], v178
	ds_read_b128 v[180:183], v178 offset:1024
	ds_read_b128 v[184:187], v178 offset:2048
	ds_read_b128 v[188:191], v178 offset:3072
	s_add_u32 s40, s36, 0xfff00080
	s_addc_u32 s41, s37, -1
	s_cmp_eq_u32 s58, 60
	s_cselect_b32 s43, s15, s41
	s_cselect_b32 s42, s17, s40
	s_cselect_b32 s41, s54, s57
	s_cselect_b32 s40, s55, s56
	ds_read_b128 v[196:199], v179
	ds_read_b128 v[200:203], v179 offset:1024
	ds_read_b128 v[204:207], v179 offset:2048
	ds_read_b128 v[208:211], v179 offset:3072
	ds_read_b128 v[212:215], v179 offset:4096
	ds_read_b128 v[220:223], v179 offset:5120
	ds_read_b128 v[224:227], v179 offset:6144
	ds_read_b128 v[228:231], v179 offset:7168
	s_add_i32 m0, s24, 0xc000
	s_nop 0
	global_load_lds_dwordx4 v146, s[36:37]
	s_add_i32 m0, s24, 0xe000
	s_nop 0
	global_load_lds_dwordx4 v150, s[36:37]
	s_sleep 2
	s_waitcnt lgkmcnt(0)
	s_waitcnt vmcnt(8)
	s_barrier
	s_setprio 2
	.p2align 3
	v_mfma_f32_16x16x32_bf16 v[126:129], v[130:133], v[196:199], v[126:129]
	v_mfma_f32_16x16x32_bf16 v[126:129], v[134:137], v[200:203], v[126:129]
	v_mfma_f32_16x16x32_bf16 v[122:125], v[138:141], v[196:199], v[122:125]
	v_mfma_f32_16x16x32_bf16 v[122:125], v[142:145], v[200:203], v[122:125]
	v_mfma_f32_16x16x32_bf16 v[118:121], v[162:165], v[196:199], v[118:121]
	v_mfma_f32_16x16x32_bf16 v[118:121], v[180:183], v[200:203], v[118:121]
	v_mfma_f32_16x16x32_bf16 v[114:117], v[184:187], v[196:199], v[114:117]
	v_mfma_f32_16x16x32_bf16 v[114:117], v[188:191], v[200:203], v[114:117]
	v_mfma_f32_16x16x32_bf16 v[98:101], v[184:187], v[204:207], v[98:101]
	v_mfma_f32_16x16x32_bf16 v[98:101], v[188:191], v[208:211], v[98:101]
	v_mfma_f32_16x16x32_bf16 v[102:105], v[162:165], v[204:207], v[102:105]
	v_mfma_f32_16x16x32_bf16 v[102:105], v[180:183], v[208:211], v[102:105]
	v_mfma_f32_16x16x32_bf16 v[106:109], v[138:141], v[204:207], v[106:109]
	v_mfma_f32_16x16x32_bf16 v[106:109], v[142:145], v[208:211], v[106:109]
	v_mfma_f32_16x16x32_bf16 v[110:113], v[130:133], v[204:207], v[110:113]
	v_mfma_f32_16x16x32_bf16 v[110:113], v[134:137], v[208:211], v[110:113]
	v_mfma_f32_16x16x32_bf16 v[94:97], v[130:133], v[212:215], v[94:97]
	v_mfma_f32_16x16x32_bf16 v[94:97], v[134:137], v[220:223], v[94:97]
	v_mfma_f32_16x16x32_bf16 v[90:93], v[138:141], v[212:215], v[90:93]
	v_mfma_f32_16x16x32_bf16 v[90:93], v[142:145], v[220:223], v[90:93]
	v_mfma_f32_16x16x32_bf16 v[86:89], v[162:165], v[212:215], v[86:89]
	v_mfma_f32_16x16x32_bf16 v[86:89], v[180:183], v[220:223], v[86:89]
	v_mfma_f32_16x16x32_bf16 v[82:85], v[184:187], v[212:215], v[82:85]
	v_mfma_f32_16x16x32_bf16 v[82:85], v[188:191], v[220:223], v[82:85]
	v_mfma_f32_16x16x32_bf16 v[66:69], v[184:187], v[224:227], v[66:69]
	v_mfma_f32_16x16x32_bf16 v[66:69], v[188:191], v[228:231], v[66:69]
	v_mfma_f32_16x16x32_bf16 v[70:73], v[162:165], v[224:227], v[70:73]
	v_mfma_f32_16x16x32_bf16 v[70:73], v[180:183], v[228:231], v[70:73]
	v_mfma_f32_16x16x32_bf16 v[74:77], v[138:141], v[224:227], v[74:77]
	v_mfma_f32_16x16x32_bf16 v[74:77], v[142:145], v[228:231], v[74:77]
	v_mfma_f32_16x16x32_bf16 v[78:81], v[130:133], v[224:227], v[78:81]
	v_mfma_f32_16x16x32_bf16 v[78:81], v[134:137], v[228:231], v[78:81]
	s_setprio 0
	ds_read_b128 v[196:199], v179 offset:16384
	ds_read_b128 v[200:203], v179 offset:17408
	ds_read_b128 v[204:207], v179 offset:18432
	ds_read_b128 v[208:211], v179 offset:19456
	ds_read_b128 v[212:215], v179 offset:20480
	ds_read_b128 v[220:223], v179 offset:21504
	ds_read_b128 v[224:227], v179 offset:22528
	ds_read_b128 v[228:231], v179 offset:23552
	s_add_u32 vcc_lo, s40, 0x100000
	s_addc_u32 vcc_hi, s41, 0
	s_add_i32 m0, s24, 0x10000
	s_nop 0
	global_load_lds_dwordx4 v148, s[40:41]
	s_add_i32 m0, s24, 0x12000
	s_nop 0
	global_load_lds_dwordx4 v152, s[40:41]
	s_add_i32 m0, s24, 0x14000
	s_nop 0
	global_load_lds_dwordx4 v148, vcc
	s_add_i32 m0, s24, 0x16000
	s_nop 0
	global_load_lds_dwordx4 v152, vcc
	s_mov_b32 m0, s24
	s_nop 0
	global_load_lds_dwordx4 v146, s[42:43]
	s_add_i32 m0, s24, 0x2000
	s_nop 0
	global_load_lds_dwordx4 v150, s[42:43]
	s_sleep 2
	s_waitcnt lgkmcnt(0)
	s_waitcnt vmcnt(8)
	s_barrier
; #define PG8_STAGE(bufoff, gbase, voff) do { _Pragma("unroll") for (int _i = 0; _i < 2; ++_i) \
;         __builtin_amdgcn_global_load_lds((const unsigned*)((const char*)(gbase) + (voff)[_i]), (PG8_LAS unsigned*)(lds + (bufoff) + ldsw + _i * 8192), 16, 0, 0); } while (0)
; #define PG8_LDA(dst, b, h) do { _Pragma("unroll") for (int m = 0; m < 4; ++m) _Pragma("unroll") for (int k = 0; k < 2; ++k) dst[m][k] = *(const PG8_LAS bf16x8*)(lds + PG8_SA(b, h) + aoff + m * 2048 + k * 1024); } while (0)
; #define PG8_LDB(dst, b, h) do { _Pragma("unroll") for (int n = 0; n < 2; ++n) _Pragma("unroll") for (int k = 0; k < 2; ++k) dst[n][k] = *(const PG8_LAS bf16x8*)(lds + PG8_SB(b, h) + boff + n * 2048 + k * 1024); } while (0)
; #define PG8_MMA(ai, bj, At, Bt) do { __builtin_amdgcn_s_setprio(1); _Pragma("unroll") for (int m = 0; m < 4; ++m) _Pragma("unroll") for (int n = 0; n < 2; ++n) _Pragma("unroll") for (int k = 0; k < 2; ++k) \
;         acc[ai][bj][m][n] = __builtin_amdgcn_mfma_f32_16x16x32_bf16(Bt[n][k], At[m][k], acc[ai][bj][m][n], 0, 0, 0); __builtin_amdgcn_s_setprio(0); } while (0)
; #define PG8_WAIT_V(n) asm volatile("s_waitcnt vmcnt(" #n ")" ::: "memory")
; #define PG8_WAIT_L(n) asm volatile("s_waitcnt lgkmcnt(" #n ")" ::: "memory")
; #define PG8_BAR __builtin_amdgcn_s_barrier()
; #define PG8_SCHED __builtin_amdgcn_sched_barrier(0)
; template <class Epi, class Sched, bool ALIGN_EPI = false, bool SP2 = false>
; __device__ __forceinline__ void gemm_phase(PG8_LAS unsigned char* lds, const Gemm g, const Sched& S, const Epi& E) {
;     ...
;             PG8_WAIT_V(8); PG8_WAIT_L(0); PG8_BAR; PG8_MMA(1, 0, At, B0); PG8_MMA(1, 1, At, B1); PG8_BAR; PG8_SCHED;
;             PG8_LDB(B0, 1, 0); PG8_LDB(B1, 1, 1); PG8_SCHED; PG8_LDA(At, 1, 0); PG8_STAGE(PG8_SA(0, 1), a2 + hstep, voffA);
	s_setprio 2
	.p2align 3
	v_mfma_f32_16x16x32_bf16 v[62:65], v[130:133], v[196:199], v[62:65]
	v_mfma_f32_16x16x32_bf16 v[62:65], v[134:137], v[200:203], v[62:65]
	v_mfma_f32_16x16x32_bf16 v[58:61], v[138:141], v[196:199], v[58:61]
	v_mfma_f32_16x16x32_bf16 v[58:61], v[142:145], v[200:203], v[58:61]
	v_mfma_f32_16x16x32_bf16 v[54:57], v[162:165], v[196:199], v[54:57]
	v_mfma_f32_16x16x32_bf16 v[54:57], v[180:183], v[200:203], v[54:57]
	v_mfma_f32_16x16x32_bf16 v[50:53], v[184:187], v[196:199], v[50:53]
	v_mfma_f32_16x16x32_bf16 v[50:53], v[188:191], v[200:203], v[50:53]
	v_mfma_f32_16x16x32_bf16 v[34:37], v[184:187], v[204:207], v[34:37]
	v_mfma_f32_16x16x32_bf16 v[34:37], v[188:191], v[208:211], v[34:37]
	v_mfma_f32_16x16x32_bf16 v[38:41], v[162:165], v[204:207], v[38:41]
	v_mfma_f32_16x16x32_bf16 v[38:41], v[180:183], v[208:211], v[38:41]
	v_mfma_f32_16x16x32_bf16 v[42:45], v[138:141], v[204:207], v[42:45]
	v_mfma_f32_16x16x32_bf16 v[42:45], v[142:145], v[208:211], v[42:45]
	v_mfma_f32_16x16x32_bf16 v[46:49], v[130:133], v[204:207], v[46:49]
	v_mfma_f32_16x16x32_bf16 v[46:49], v[134:137], v[208:211], v[46:49]
	v_mfma_f32_16x16x32_bf16 v[30:33], v[130:133], v[212:215], v[30:33]
	v_mfma_f32_16x16x32_bf16 v[30:33], v[134:137], v[220:223], v[30:33]
	v_mfma_f32_16x16x32_bf16 v[26:29], v[138:141], v[212:215], v[26:29]
	v_mfma_f32_16x16x32_bf16 v[26:29], v[142:145], v[220:223], v[26:29]
	v_mfma_f32_16x16x32_bf16 v[22:25], v[162:165], v[212:215], v[22:25]
	v_mfma_f32_16x16x32_bf16 v[22:25], v[180:183], v[220:223], v[22:25]
	v_mfma_f32_16x16x32_bf16 v[18:21], v[184:187], v[212:215], v[18:21]
	v_mfma_f32_16x16x32_bf16 v[18:21], v[188:191], v[220:223], v[18:21]
	v_mfma_f32_16x16x32_bf16 v[2:5], v[184:187], v[224:227], v[2:5]
	v_mfma_f32_16x16x32_bf16 v[2:5], v[188:191], v[228:231], v[2:5]
	v_mfma_f32_16x16x32_bf16 v[6:9], v[162:165], v[224:227], v[6:9]
	v_mfma_f32_16x16x32_bf16 v[6:9], v[180:183], v[228:231], v[6:9]
	v_mfma_f32_16x16x32_bf16 v[10:13], v[138:141], v[224:227], v[10:13]
	v_mfma_f32_16x16x32_bf16 v[10:13], v[142:145], v[228:231], v[10:13]
	v_mfma_f32_16x16x32_bf16 v[14:17], v[130:133], v[224:227], v[14:17]
	v_mfma_f32_16x16x32_bf16 v[14:17], v[134:137], v[228:231], v[14:17]
	s_setprio 0
	s_add_i32 s59, 0, 0x18000
	s_add_i32 s60, 0, 0x1c000
	v_add_u32_e32 v142, s59, v166
	v_add_u32_e32 v188, s60, v166
	ds_read_b128 v[130:133], v142
	ds_read_b128 v[134:137], v142 offset:1024
	ds_read_b128 v[138:141], v142 offset:2048
	ds_read_b128 v[142:145], v142 offset:3072
	ds_read_b128 v[162:165], v188
	ds_read_b128 v[180:183], v188 offset:1024
	ds_read_b128 v[184:187], v188 offset:2048
	ds_read_b128 v[188:191], v188 offset:3072
	ds_read_b128 v[196:199], v179 offset:32768
	ds_read_b128 v[200:203], v179 offset:33792
	ds_read_b128 v[204:207], v179 offset:34816
	ds_read_b128 v[208:211], v179 offset:35840
	ds_read_b128 v[212:215], v179 offset:36864
	ds_read_b128 v[220:223], v179 offset:37888
	ds_read_b128 v[224:227], v179 offset:38912
	ds_read_b128 v[228:231], v179 offset:39936
	s_add_u32 vcc_lo, s42, 0x100000
	s_addc_u32 vcc_hi, s43, 0
	s_add_i32 m0, s24, 0x4000
	s_nop 0
	global_load_lds_dwordx4 v146, vcc
	s_add_i32 m0, s24, 0x6000
	s_nop 0
	global_load_lds_dwordx4 v150, vcc
	s_sleep 2
	s_waitcnt lgkmcnt(0)
	s_waitcnt vmcnt(8)
	s_barrier
; #define PG8_STAGE(bufoff, gbase, voff) do { _Pragma("unroll") for (int _i = 0; _i < 2; ++_i) \
;         __builtin_amdgcn_global_load_lds((const unsigned*)((const char*)(gbase) + (voff)[_i]), (PG8_LAS unsigned*)(lds + (bufoff) + ldsw + _i * 8192), 16, 0, 0); } while (0)
; #define PG8_LDA(dst, b, h) do { _Pragma("unroll") for (int m = 0; m < 4; ++m) _Pragma("unroll") for (int k = 0; k < 2; ++k) dst[m][k] = *(const PG8_LAS bf16x8*)(lds + PG8_SA(b, h) + aoff + m * 2048 + k * 1024); } while (0)
; #define PG8_MMA(ai, bj, At, Bt) do { __builtin_amdgcn_s_setprio(1); _Pragma("unroll") for (int m = 0; m < 4; ++m) _Pragma("unroll") for (int n = 0; n < 2; ++n) _Pragma("unroll") for (int k = 0; k < 2; ++k) \
;         acc[ai][bj][m][n] = __builtin_amdgcn_mfma_f32_16x16x32_bf16(Bt[n][k], At[m][k], acc[ai][bj][m][n], 0, 0, 0); __builtin_amdgcn_s_setprio(0); } while (0)
; #define PG8_WAIT_V(n) asm volatile("s_waitcnt vmcnt(" #n ")" ::: "memory")
; #define PG8_WAIT_L(n) asm volatile("s_waitcnt lgkmcnt(" #n ")" ::: "memory")
; #define PG8_BAR __builtin_amdgcn_s_barrier()
; #define PG8_SCHED __builtin_amdgcn_sched_barrier(0)
; template <class Epi, class Sched, bool ALIGN_EPI = false, bool SP2 = false>
; __device__ __forceinline__ void gemm_phase(PG8_LAS unsigned char* lds, const Gemm g, const Sched& S, const Epi& E) {
;     ...
;         for (int t = 0; t < nt; t += 2) {
;             const bool last = (t == nt - 2);
;     ...
;             PG8_WAIT_V(8); PG8_WAIT_L(0); PG8_BAR; PG8_MMA(0, 0, At, B0); PG8_MMA(0, 1, At, B1); PG8_BAR; PG8_SCHED;
;             PG8_LDA(At, 1, 1); PG8_STAGE(PG8_SB(1, 0), b3, voffB); PG8_STAGE(PG8_SB(1, 1), b3 + hstep, voffB); PG8_STAGE(PG8_SA(1, 0), a3, voffA);
;             PG8_WAIT_V(8); PG8_WAIT_L(0); PG8_BAR; PG8_MMA(1, 0, At, B0); PG8_MMA(1, 1, At, B1); PG8_BAR; PG8_SCHED;
	s_setprio 2
	.p2align 3
	v_mfma_f32_16x16x32_bf16 v[126:129], v[130:133], v[196:199], v[126:129]
	v_mfma_f32_16x16x32_bf16 v[126:129], v[134:137], v[200:203], v[126:129]
	v_mfma_f32_16x16x32_bf16 v[122:125], v[138:141], v[196:199], v[122:125]
	v_mfma_f32_16x16x32_bf16 v[122:125], v[142:145], v[200:203], v[122:125]
	v_mfma_f32_16x16x32_bf16 v[118:121], v[162:165], v[196:199], v[118:121]
	v_mfma_f32_16x16x32_bf16 v[118:121], v[180:183], v[200:203], v[118:121]
	v_mfma_f32_16x16x32_bf16 v[114:117], v[184:187], v[196:199], v[114:117]
	v_mfma_f32_16x16x32_bf16 v[114:117], v[188:191], v[200:203], v[114:117]
	v_mfma_f32_16x16x32_bf16 v[98:101], v[184:187], v[204:207], v[98:101]
	v_mfma_f32_16x16x32_bf16 v[98:101], v[188:191], v[208:211], v[98:101]
	v_mfma_f32_16x16x32_bf16 v[102:105], v[162:165], v[204:207], v[102:105]
	v_mfma_f32_16x16x32_bf16 v[102:105], v[180:183], v[208:211], v[102:105]
	v_mfma_f32_16x16x32_bf16 v[106:109], v[138:141], v[204:207], v[106:109]
	v_mfma_f32_16x16x32_bf16 v[106:109], v[142:145], v[208:211], v[106:109]
	v_mfma_f32_16x16x32_bf16 v[110:113], v[130:133], v[204:207], v[110:113]
	v_mfma_f32_16x16x32_bf16 v[110:113], v[134:137], v[208:211], v[110:113]
	v_mfma_f32_16x16x32_bf16 v[94:97], v[130:133], v[212:215], v[94:97]
	v_mfma_f32_16x16x32_bf16 v[94:97], v[134:137], v[220:223], v[94:97]
	v_mfma_f32_16x16x32_bf16 v[90:93], v[138:141], v[212:215], v[90:93]
	v_mfma_f32_16x16x32_bf16 v[90:93], v[142:145], v[220:223], v[90:93]
	v_mfma_f32_16x16x32_bf16 v[86:89], v[162:165], v[212:215], v[86:89]
	v_mfma_f32_16x16x32_bf16 v[86:89], v[180:183], v[220:223], v[86:89]
	v_mfma_f32_16x16x32_bf16 v[82:85], v[184:187], v[212:215], v[82:85]
	v_mfma_f32_16x16x32_bf16 v[82:85], v[188:191], v[220:223], v[82:85]
	v_mfma_f32_16x16x32_bf16 v[66:69], v[184:187], v[224:227], v[66:69]
	v_mfma_f32_16x16x32_bf16 v[66:69], v[188:191], v[228:231], v[66:69]
	v_mfma_f32_16x16x32_bf16 v[70:73], v[162:165], v[224:227], v[70:73]
	v_mfma_f32_16x16x32_bf16 v[70:73], v[180:183], v[228:231], v[70:73]
	v_mfma_f32_16x16x32_bf16 v[74:77], v[138:141], v[224:227], v[74:77]
	v_mfma_f32_16x16x32_bf16 v[74:77], v[142:145], v[228:231], v[74:77]
	v_mfma_f32_16x16x32_bf16 v[78:81], v[130:133], v[224:227], v[78:81]
	v_mfma_f32_16x16x32_bf16 v[78:81], v[134:137], v[228:231], v[78:81]
	s_setprio 0
	ds_read_b128 v[196:199], v179 offset:49152
	ds_read_b128 v[200:203], v179 offset:50176
	ds_read_b128 v[204:207], v179 offset:51200
	ds_read_b128 v[208:211], v179 offset:52224
	ds_read_b128 v[212:215], v179 offset:53248
	ds_read_b128 v[220:223], v179 offset:54272
	ds_read_b128 v[224:227], v179 offset:55296
	ds_read_b128 v[228:231], v179 offset:56320
	s_add_u32 s60, s40, 0x80
	s_addc_u32 s61, s41, 0
	s_add_u32 vcc_lo, s60, 0x100000
	s_addc_u32 vcc_hi, s61, 0
	s_add_i32 m0, s24, 0x18000
	s_nop 0
	global_load_lds_dwordx4 v148, s[60:61]
	s_add_i32 m0, s24, 0x1a000
	s_nop 0
	global_load_lds_dwordx4 v152, s[60:61]
	s_add_i32 m0, s24, 0x1c000
	s_nop 0
	global_load_lds_dwordx4 v148, vcc
	s_add_i32 m0, s24, 0x1e000
	s_nop 0
	global_load_lds_dwordx4 v152, vcc
	s_add_u32 s60, s42, 0x80
	s_addc_u32 s61, s43, 0
	s_add_i32 m0, s24, 0x8000
	s_nop 0
	global_load_lds_dwordx4 v146, s[60:61]
	s_add_i32 m0, s24, 0xa000
	s_nop 0
	global_load_lds_dwordx4 v150, s[60:61]
	s_sleep 2
	s_waitcnt lgkmcnt(0)
	s_waitcnt vmcnt(8)
	s_barrier
	s_setprio 2
	.p2align 3
	v_mfma_f32_16x16x32_bf16 v[62:65], v[130:133], v[196:199], v[62:65]
	v_mfma_f32_16x16x32_bf16 v[62:65], v[134:137], v[200:203], v[62:65]
	v_mfma_f32_16x16x32_bf16 v[58:61], v[138:141], v[196:199], v[58:61]
	v_mfma_f32_16x16x32_bf16 v[58:61], v[142:145], v[200:203], v[58:61]
	v_mfma_f32_16x16x32_bf16 v[54:57], v[162:165], v[196:199], v[54:57]
	v_mfma_f32_16x16x32_bf16 v[54:57], v[180:183], v[200:203], v[54:57]
	v_mfma_f32_16x16x32_bf16 v[50:53], v[184:187], v[196:199], v[50:53]
	v_mfma_f32_16x16x32_bf16 v[50:53], v[188:191], v[200:203], v[50:53]
	v_mfma_f32_16x16x32_bf16 v[34:37], v[184:187], v[204:207], v[34:37]
	v_mfma_f32_16x16x32_bf16 v[34:37], v[188:191], v[208:211], v[34:37]
	v_mfma_f32_16x16x32_bf16 v[38:41], v[162:165], v[204:207], v[38:41]
	v_mfma_f32_16x16x32_bf16 v[38:41], v[180:183], v[208:211], v[38:41]
	v_mfma_f32_16x16x32_bf16 v[42:45], v[138:141], v[204:207], v[42:45]
	v_mfma_f32_16x16x32_bf16 v[42:45], v[142:145], v[208:211], v[42:45]
	v_mfma_f32_16x16x32_bf16 v[46:49], v[130:133], v[204:207], v[46:49]
	v_mfma_f32_16x16x32_bf16 v[46:49], v[134:137], v[208:211], v[46:49]
	v_mfma_f32_16x16x32_bf16 v[30:33], v[130:133], v[212:215], v[30:33]
	v_mfma_f32_16x16x32_bf16 v[30:33], v[134:137], v[220:223], v[30:33]
	v_mfma_f32_16x16x32_bf16 v[26:29], v[138:141], v[212:215], v[26:29]
	v_mfma_f32_16x16x32_bf16 v[26:29], v[142:145], v[220:223], v[26:29]
	v_mfma_f32_16x16x32_bf16 v[22:25], v[162:165], v[212:215], v[22:25]
	v_mfma_f32_16x16x32_bf16 v[22:25], v[180:183], v[220:223], v[22:25]
	v_mfma_f32_16x16x32_bf16 v[18:21], v[184:187], v[212:215], v[18:21]
	v_mfma_f32_16x16x32_bf16 v[18:21], v[188:191], v[220:223], v[18:21]
	v_mfma_f32_16x16x32_bf16 v[2:5], v[184:187], v[224:227], v[2:5]
	v_mfma_f32_16x16x32_bf16 v[2:5], v[188:191], v[228:231], v[2:5]
	v_mfma_f32_16x16x32_bf16 v[6:9], v[162:165], v[224:227], v[6:9]
	v_mfma_f32_16x16x32_bf16 v[6:9], v[180:183], v[228:231], v[6:9]
	v_mfma_f32_16x16x32_bf16 v[10:13], v[138:141], v[224:227], v[10:13]
	v_mfma_f32_16x16x32_bf16 v[10:13], v[142:145], v[228:231], v[10:13]
	v_mfma_f32_16x16x32_bf16 v[14:17], v[130:133], v[224:227], v[14:17]
	v_mfma_f32_16x16x32_bf16 v[14:17], v[134:137], v[228:231], v[14:17]
	s_setprio 0
	s_add_i32 s58, s58, 2
	s_add_u32 s36, s36, 0x100
	s_addc_u32 s37, s37, 0
	s_add_u32 s56, s56, 0x100
	s_addc_u32 s57, s57, 0
	s_cmp_gt_u32 s58, 61
	s_cbranch_scc0 .Lf1_h1

; #define PG8_STAGE(bufoff, gbase, voff) do { _Pragma("unroll") for (int _i = 0; _i < 2; ++_i) \
;         __builtin_amdgcn_global_load_lds((const unsigned*)((const char*)(gbase) + (voff)[_i]), (PG8_LAS unsigned*)(lds + (bufoff) + ldsw + _i * 8192), 16, 0, 0); } while (0)
; #define PG8_LDA(dst, b, h) do { _Pragma("unroll") for (int m = 0; m < 4; ++m) _Pragma("unroll") for (int k = 0; k < 2; ++k) dst[m][k] = *(const PG8_LAS bf16x8*)(lds + PG8_SA(b, h) + aoff + m * 2048 + k * 1024); } while (0)
; #define PG8_LDB(dst, b, h) do { _Pragma("unroll") for (int n = 0; n < 2; ++n) _Pragma("unroll") for (int k = 0; k < 2; ++k) dst[n][k] = *(const PG8_LAS bf16x8*)(lds + PG8_SB(b, h) + boff + n * 2048 + k * 1024); } while (0)
; #define PG8_MMA(ai, bj, At, Bt) do { __builtin_amdgcn_s_setprio(1); _Pragma("unroll") for (int m = 0; m < 4; ++m) _Pragma("unroll") for (int n = 0; n < 2; ++n) _Pragma("unroll") for (int k = 0; k < 2; ++k) \
;         acc[ai][bj][m][n] = __builtin_amdgcn_mfma_f32_16x16x32_bf16(Bt[n][k], At[m][k], acc[ai][bj][m][n], 0, 0, 0); __builtin_amdgcn_s_setprio(0); } while (0)
; #define PG8_WAIT_V(n) asm volatile("s_waitcnt vmcnt(" #n ")" ::: "memory")
; #define PG8_WAIT_L(n) asm volatile("s_waitcnt lgkmcnt(" #n ")" ::: "memory")
; #define PG8_BAR __builtin_amdgcn_s_barrier()
; #define PG8_SCHED __builtin_amdgcn_sched_barrier(0)
; template <class Epi, class Sched, bool ALIGN_EPI = false, bool SP2 = false>
; __device__ __forceinline__ void gemm_phase(PG8_LAS unsigned char* lds, const Gemm g, const Sched& S, const Epi& E) {
;     ...
;             PG8_LDB(B0, 0, 0); PG8_LDB(B1, 0, 1); PG8_SCHED; PG8_LDA(At, 0, 0); PG8_STAGE(PG8_SA(1, 1), a1 + hstep, voffA);
;             PG8_WAIT_V(8); PG8_WAIT_L(0); PG8_BAR; PG8_MMA(0, 0, At, B0); PG8_MMA(0, 1, At, B1); PG8_BAR; PG8_SCHED;
;             PG8_LDA(At, 0, 1); PG8_STAGE(PG8_SB(0, 0), b2, voffB); PG8_STAGE(PG8_SB(0, 1), b2 + hstep, voffB); PG8_STAGE(PG8_SA(0, 0), a2, voffA);
;             PG8_WAIT_V(8); PG8_WAIT_L(0); PG8_BAR; PG8_MMA(1, 0, At, B0); PG8_MMA(1, 1, At, B1); PG8_BAR; PG8_SCHED;
.LBB0_1321:
	ds_read_b128 v[128:131], v156
	ds_read_b128 v[132:135], v156 offset:1024
	ds_read_b128 v[150:153], v156 offset:2048
	ds_read_b128 v[162:165], v156 offset:3072
	ds_read_b128 v[166:169], v157
	ds_read_b128 v[170:173], v157 offset:1024
	ds_read_b128 v[174:177], v157 offset:2048
	ds_read_b128 v[178:181], v157 offset:3072
	s_add_u32 s20, s18, 0xffbfc080
	s_addc_u32 s21, s19, -1
	s_cmpk_eq_i32 s59, 0xfc
	s_cselect_b32 s23, s7, s21
	s_cselect_b32 s22, s6, s20
	s_cselect_b32 s21, s17, s58
	s_cselect_b32 s20, s16, s57
	ds_read_b128 v[182:185], v158
	ds_read_b128 v[186:189], v158 offset:1024
	ds_read_b128 v[190:193], v158 offset:2048
	ds_read_b128 v[194:197], v158 offset:3072
	ds_read_b128 v[198:201], v158 offset:4096
	ds_read_b128 v[202:205], v158 offset:5120
	ds_read_b128 v[206:209], v158 offset:6144
	ds_read_b128 v[210:213], v158 offset:7168
	s_add_i32 m0, s24, 0xc000
	s_nop 0
	global_load_lds_dwordx4 v136, s[18:19]
	s_add_i32 m0, s24, 0xe000
	s_nop 0
	global_load_lds_dwordx4 v140, s[18:19]
	s_waitcnt lgkmcnt(0)
	s_setprio 1
	.p2align 3
	v_mfma_f32_16x16x32_bf16 v[124:127], v[128:131], v[182:185], v[124:127]
	v_mfma_f32_16x16x32_bf16 v[124:127], v[132:135], v[186:189], v[124:127]
	v_mfma_f32_16x16x32_bf16 v[120:123], v[150:153], v[182:185], v[120:123]
	v_mfma_f32_16x16x32_bf16 v[120:123], v[162:165], v[186:189], v[120:123]
	v_mfma_f32_16x16x32_bf16 v[68:71], v[166:169], v[182:185], v[68:71]
	v_mfma_f32_16x16x32_bf16 v[68:71], v[170:173], v[186:189], v[68:71]
	v_mfma_f32_16x16x32_bf16 v[64:67], v[174:177], v[182:185], v[64:67]
	v_mfma_f32_16x16x32_bf16 v[64:67], v[178:181], v[186:189], v[64:67]
	v_mfma_f32_16x16x32_bf16 v[48:51], v[174:177], v[190:193], v[48:51]
	v_mfma_f32_16x16x32_bf16 v[48:51], v[178:181], v[194:197], v[48:51]
	v_mfma_f32_16x16x32_bf16 v[52:55], v[166:169], v[190:193], v[52:55]
	v_mfma_f32_16x16x32_bf16 v[52:55], v[170:173], v[194:197], v[52:55]
	v_mfma_f32_16x16x32_bf16 v[112:115], v[150:153], v[190:193], v[112:115]
	v_mfma_f32_16x16x32_bf16 v[112:115], v[162:165], v[194:197], v[112:115]
	v_mfma_f32_16x16x32_bf16 v[116:119], v[128:131], v[190:193], v[116:119]
	v_mfma_f32_16x16x32_bf16 v[116:119], v[132:135], v[194:197], v[116:119]
	v_mfma_f32_16x16x32_bf16 v[108:111], v[128:131], v[198:201], v[108:111]
	v_mfma_f32_16x16x32_bf16 v[108:111], v[132:135], v[202:205], v[108:111]
	v_mfma_f32_16x16x32_bf16 v[104:107], v[150:153], v[198:201], v[104:107]
	v_mfma_f32_16x16x32_bf16 v[104:107], v[162:165], v[202:205], v[104:107]
	v_mfma_f32_16x16x32_bf16 v[44:47], v[166:169], v[198:201], v[44:47]
	v_mfma_f32_16x16x32_bf16 v[44:47], v[170:173], v[202:205], v[44:47]
	v_mfma_f32_16x16x32_bf16 v[40:43], v[174:177], v[198:201], v[40:43]
	v_mfma_f32_16x16x32_bf16 v[40:43], v[178:181], v[202:205], v[40:43]
	v_mfma_f32_16x16x32_bf16 v[32:35], v[174:177], v[206:209], v[32:35]
	v_mfma_f32_16x16x32_bf16 v[32:35], v[178:181], v[210:213], v[32:35]
	v_mfma_f32_16x16x32_bf16 v[36:39], v[166:169], v[206:209], v[36:39]
	v_mfma_f32_16x16x32_bf16 v[36:39], v[170:173], v[210:213], v[36:39]
	v_mfma_f32_16x16x32_bf16 v[96:99], v[150:153], v[206:209], v[96:99]
	v_mfma_f32_16x16x32_bf16 v[96:99], v[162:165], v[210:213], v[96:99]
	v_mfma_f32_16x16x32_bf16 v[100:103], v[128:131], v[206:209], v[100:103]
	v_mfma_f32_16x16x32_bf16 v[100:103], v[132:135], v[210:213], v[100:103]
	s_setprio 0
	s_waitcnt vmcnt(8)
	s_barrier
	ds_read_b128 v[182:185], v158 offset:16384
	ds_read_b128 v[186:189], v158 offset:17408
	ds_read_b128 v[190:193], v158 offset:18432
	ds_read_b128 v[194:197], v158 offset:19456
	ds_read_b128 v[198:201], v158 offset:20480
	ds_read_b128 v[202:205], v158 offset:21504
	ds_read_b128 v[206:209], v158 offset:22528
	ds_read_b128 v[210:213], v158 offset:23552
	s_add_u32 vcc_lo, s20, 0x404000
	s_addc_u32 vcc_hi, s21, 0
	s_add_i32 m0, s24, 0x10000
	s_nop 0
	global_load_lds_dwordx4 v138, s[20:21]
	s_add_i32 m0, s24, 0x12000
	s_nop 0
	global_load_lds_dwordx4 v142, s[20:21]
	s_add_i32 m0, s24, 0x14000
	s_nop 0
	global_load_lds_dwordx4 v138, vcc
	s_add_i32 m0, s24, 0x16000
	s_nop 0
	global_load_lds_dwordx4 v142, vcc
	s_mov_b32 m0, s24
	s_nop 0
	global_load_lds_dwordx4 v136, s[22:23]
	s_add_i32 m0, s24, 0x2000
	s_nop 0
	global_load_lds_dwordx4 v140, s[22:23]
	s_waitcnt lgkmcnt(0)
	s_setprio 1
	.p2align 3
	v_mfma_f32_16x16x32_bf16 v[92:95], v[128:131], v[182:185], v[92:95]
	v_mfma_f32_16x16x32_bf16 v[92:95], v[132:135], v[186:189], v[92:95]
	v_mfma_f32_16x16x32_bf16 v[88:91], v[150:153], v[182:185], v[88:91]
	v_mfma_f32_16x16x32_bf16 v[88:91], v[162:165], v[186:189], v[88:91]
	v_mfma_f32_16x16x32_bf16 v[28:31], v[166:169], v[182:185], v[28:31]
	v_mfma_f32_16x16x32_bf16 v[28:31], v[170:173], v[186:189], v[28:31]
	v_mfma_f32_16x16x32_bf16 v[24:27], v[174:177], v[182:185], v[24:27]
	v_mfma_f32_16x16x32_bf16 v[24:27], v[178:181], v[186:189], v[24:27]
	v_mfma_f32_16x16x32_bf16 v[16:19], v[174:177], v[190:193], v[16:19]
	v_mfma_f32_16x16x32_bf16 v[16:19], v[178:181], v[194:197], v[16:19]
	v_mfma_f32_16x16x32_bf16 v[20:23], v[166:169], v[190:193], v[20:23]
	v_mfma_f32_16x16x32_bf16 v[20:23], v[170:173], v[194:197], v[20:23]
	v_mfma_f32_16x16x32_bf16 v[80:83], v[150:153], v[190:193], v[80:83]
	v_mfma_f32_16x16x32_bf16 v[80:83], v[162:165], v[194:197], v[80:83]
	v_mfma_f32_16x16x32_bf16 v[84:87], v[128:131], v[190:193], v[84:87]
	v_mfma_f32_16x16x32_bf16 v[84:87], v[132:135], v[194:197], v[84:87]
	v_mfma_f32_16x16x32_bf16 v[76:79], v[128:131], v[198:201], v[76:79]
	v_mfma_f32_16x16x32_bf16 v[76:79], v[132:135], v[202:205], v[76:79]
	v_mfma_f32_16x16x32_bf16 v[72:75], v[150:153], v[198:201], v[72:75]
	v_mfma_f32_16x16x32_bf16 v[72:75], v[162:165], v[202:205], v[72:75]
	v_mfma_f32_16x16x32_bf16 v[12:15], v[166:169], v[198:201], v[12:15]
	v_mfma_f32_16x16x32_bf16 v[12:15], v[170:173], v[202:205], v[12:15]
	v_mfma_f32_16x16x32_bf16 v[8:11], v[174:177], v[198:201], v[8:11]
	v_mfma_f32_16x16x32_bf16 v[8:11], v[178:181], v[202:205], v[8:11]
	v_mfma_f32_16x16x32_bf16 v[0:3], v[174:177], v[206:209], v[0:3]
	v_mfma_f32_16x16x32_bf16 v[0:3], v[178:181], v[210:213], v[0:3]
	v_mfma_f32_16x16x32_bf16 v[4:7], v[166:169], v[206:209], v[4:7]
	v_mfma_f32_16x16x32_bf16 v[4:7], v[170:173], v[210:213], v[4:7]
	v_mfma_f32_16x16x32_bf16 v[56:59], v[150:153], v[206:209], v[56:59]
	v_mfma_f32_16x16x32_bf16 v[56:59], v[162:165], v[210:213], v[56:59]
	v_mfma_f32_16x16x32_bf16 v[60:63], v[128:131], v[206:209], v[60:63]
	v_mfma_f32_16x16x32_bf16 v[60:63], v[132:135], v[210:213], v[60:63]
	s_setprio 0
	s_waitcnt vmcnt(8)
	s_barrier
; #define PG8_STAGE(bufoff, gbase, voff) do { _Pragma("unroll") for (int _i = 0; _i < 2; ++_i) \
;         __builtin_amdgcn_global_load_lds((const unsigned*)((const char*)(gbase) + (voff)[_i]), (PG8_LAS unsigned*)(lds + (bufoff) + ldsw + _i * 8192), 16, 0, 0); } while (0)
; #define PG8_LDA(dst, b, h) do { _Pragma("unroll") for (int m = 0; m < 4; ++m) _Pragma("unroll") for (int k = 0; k < 2; ++k) dst[m][k] = *(const PG8_LAS bf16x8*)(lds + PG8_SA(b, h) + aoff + m * 2048 + k * 1024); } while (0)
; #define PG8_LDB(dst, b, h) do { _Pragma("unroll") for (int n = 0; n < 2; ++n) _Pragma("unroll") for (int k = 0; k < 2; ++k) dst[n][k] = *(const PG8_LAS bf16x8*)(lds + PG8_SB(b, h) + boff + n * 2048 + k * 1024); } while (0)
; #define PG8_MMA(ai, bj, At, Bt) do { __builtin_amdgcn_s_setprio(1); _Pragma("unroll") for (int m = 0; m < 4; ++m) _Pragma("unroll") for (int n = 0; n < 2; ++n) _Pragma("unroll") for (int k = 0; k < 2; ++k) \
;         acc[ai][bj][m][n] = __builtin_amdgcn_mfma_f32_16x16x32_bf16(Bt[n][k], At[m][k], acc[ai][bj][m][n], 0, 0, 0); __builtin_amdgcn_s_setprio(0); } while (0)
; #define PG8_WAIT_V(n) asm volatile("s_waitcnt vmcnt(" #n ")" ::: "memory")
; #define PG8_WAIT_L(n) asm volatile("s_waitcnt lgkmcnt(" #n ")" ::: "memory")
; #define PG8_BAR __builtin_amdgcn_s_barrier()
; #define PG8_SCHED __builtin_amdgcn_sched_barrier(0)
; template <class Epi, class Sched, bool ALIGN_EPI = false, bool SP2 = false>
; __device__ __forceinline__ void gemm_phase(PG8_LAS unsigned char* lds, const Gemm g, const Sched& S, const Epi& E) {
;     ...
;         for (int t = 0; t < nt; t += 2) {
;             const bool last = (t == nt - 2);
;     ...
;             PG8_LDB(B0, 1, 0); PG8_LDB(B1, 1, 1); PG8_SCHED; PG8_LDA(At, 1, 0); PG8_STAGE(PG8_SA(0, 1), a2 + hstep, voffA);
;             PG8_WAIT_V(8); PG8_WAIT_L(0); PG8_BAR; PG8_MMA(0, 0, At, B0); PG8_MMA(0, 1, At, B1); PG8_BAR; PG8_SCHED;
;             PG8_LDA(At, 1, 1); PG8_STAGE(PG8_SB(1, 0), b3, voffB); PG8_STAGE(PG8_SB(1, 1), b3 + hstep, voffB); PG8_STAGE(PG8_SA(1, 0), a3, voffA);
;             PG8_WAIT_V(8); PG8_WAIT_L(0); PG8_BAR; PG8_MMA(1, 0, At, B0); PG8_MMA(1, 1, At, B1); PG8_BAR; PG8_SCHED;
	ds_read_b128 v[128:131], v159
	ds_read_b128 v[132:135], v159 offset:1024
	ds_read_b128 v[150:153], v159 offset:2048
	ds_read_b128 v[162:165], v159 offset:3072
	ds_read_b128 v[166:169], v160
	ds_read_b128 v[170:173], v160 offset:1024
	ds_read_b128 v[174:177], v160 offset:2048
	ds_read_b128 v[178:181], v160 offset:3072
	ds_read_b128 v[182:185], v158 offset:32768
	ds_read_b128 v[186:189], v158 offset:33792
	ds_read_b128 v[190:193], v158 offset:34816
	ds_read_b128 v[194:197], v158 offset:35840
	ds_read_b128 v[198:201], v158 offset:36864
	ds_read_b128 v[202:205], v158 offset:37888
	ds_read_b128 v[206:209], v158 offset:38912
	ds_read_b128 v[210:213], v158 offset:39936
	s_add_u32 vcc_lo, s22, 0x404000
	s_addc_u32 vcc_hi, s23, 0
	s_add_i32 m0, s24, 0x4000
	s_nop 0
	global_load_lds_dwordx4 v136, vcc
	s_add_i32 m0, s24, 0x6000
	s_nop 0
	global_load_lds_dwordx4 v140, vcc
	s_waitcnt lgkmcnt(0)
	s_setprio 1
	.p2align 3
	v_mfma_f32_16x16x32_bf16 v[124:127], v[128:131], v[182:185], v[124:127]
	v_mfma_f32_16x16x32_bf16 v[124:127], v[132:135], v[186:189], v[124:127]
	v_mfma_f32_16x16x32_bf16 v[120:123], v[150:153], v[182:185], v[120:123]
	v_mfma_f32_16x16x32_bf16 v[120:123], v[162:165], v[186:189], v[120:123]
	v_mfma_f32_16x16x32_bf16 v[68:71], v[166:169], v[182:185], v[68:71]
	v_mfma_f32_16x16x32_bf16 v[68:71], v[170:173], v[186:189], v[68:71]
	v_mfma_f32_16x16x32_bf16 v[64:67], v[174:177], v[182:185], v[64:67]
	v_mfma_f32_16x16x32_bf16 v[64:67], v[178:181], v[186:189], v[64:67]
	v_mfma_f32_16x16x32_bf16 v[48:51], v[174:177], v[190:193], v[48:51]
	v_mfma_f32_16x16x32_bf16 v[48:51], v[178:181], v[194:197], v[48:51]
	v_mfma_f32_16x16x32_bf16 v[52:55], v[166:169], v[190:193], v[52:55]
	v_mfma_f32_16x16x32_bf16 v[52:55], v[170:173], v[194:197], v[52:55]
	v_mfma_f32_16x16x32_bf16 v[112:115], v[150:153], v[190:193], v[112:115]
	v_mfma_f32_16x16x32_bf16 v[112:115], v[162:165], v[194:197], v[112:115]
	v_mfma_f32_16x16x32_bf16 v[116:119], v[128:131], v[190:193], v[116:119]
	v_mfma_f32_16x16x32_bf16 v[116:119], v[132:135], v[194:197], v[116:119]
	v_mfma_f32_16x16x32_bf16 v[108:111], v[128:131], v[198:201], v[108:111]
	v_mfma_f32_16x16x32_bf16 v[108:111], v[132:135], v[202:205], v[108:111]
	v_mfma_f32_16x16x32_bf16 v[104:107], v[150:153], v[198:201], v[104:107]
	v_mfma_f32_16x16x32_bf16 v[104:107], v[162:165], v[202:205], v[104:107]
	v_mfma_f32_16x16x32_bf16 v[44:47], v[166:169], v[198:201], v[44:47]
	v_mfma_f32_16x16x32_bf16 v[44:47], v[170:173], v[202:205], v[44:47]
	v_mfma_f32_16x16x32_bf16 v[40:43], v[174:177], v[198:201], v[40:43]
	v_mfma_f32_16x16x32_bf16 v[40:43], v[178:181], v[202:205], v[40:43]
	v_mfma_f32_16x16x32_bf16 v[32:35], v[174:177], v[206:209], v[32:35]
	v_mfma_f32_16x16x32_bf16 v[32:35], v[178:181], v[210:213], v[32:35]
	v_mfma_f32_16x16x32_bf16 v[36:39], v[166:169], v[206:209], v[36:39]
	v_mfma_f32_16x16x32_bf16 v[36:39], v[170:173], v[210:213], v[36:39]
	v_mfma_f32_16x16x32_bf16 v[96:99], v[150:153], v[206:209], v[96:99]
	v_mfma_f32_16x16x32_bf16 v[96:99], v[162:165], v[210:213], v[96:99]
	v_mfma_f32_16x16x32_bf16 v[100:103], v[128:131], v[206:209], v[100:103]
	v_mfma_f32_16x16x32_bf16 v[100:103], v[132:135], v[210:213], v[100:103]
	s_setprio 0
	s_waitcnt vmcnt(8)
	s_barrier
	ds_read_b128 v[182:185], v158 offset:49152
	ds_read_b128 v[186:189], v158 offset:50176
	ds_read_b128 v[190:193], v158 offset:51200
	ds_read_b128 v[194:197], v158 offset:52224
	ds_read_b128 v[198:201], v158 offset:53248
	ds_read_b128 v[202:205], v158 offset:54272
	ds_read_b128 v[206:209], v158 offset:55296
	ds_read_b128 v[210:213], v158 offset:56320
	s_add_u32 s60, s20, 0x80
	s_addc_u32 s61, s21, 0
	s_add_u32 vcc_lo, s60, 0x404000
	s_addc_u32 vcc_hi, s61, 0
	s_add_i32 m0, s24, 0x18000
	s_nop 0
	global_load_lds_dwordx4 v138, s[60:61]
	s_add_i32 m0, s24, 0x1a000
	s_nop 0
	global_load_lds_dwordx4 v142, s[60:61]
	s_add_i32 m0, s24, 0x1c000
	s_nop 0
	global_load_lds_dwordx4 v138, vcc
	s_add_i32 m0, s24, 0x1e000
	s_nop 0
	global_load_lds_dwordx4 v142, vcc
	s_add_u32 s60, s22, 0x80
	s_addc_u32 s61, s23, 0
	s_add_i32 m0, s24, 0x8000
	s_nop 0
	global_load_lds_dwordx4 v136, s[60:61]
	s_add_i32 m0, s24, 0xa000
	s_nop 0
	global_load_lds_dwordx4 v140, s[60:61]
	s_waitcnt lgkmcnt(0)
	s_setprio 1
	.p2align 3
	v_mfma_f32_16x16x32_bf16 v[92:95], v[128:131], v[182:185], v[92:95]
	v_mfma_f32_16x16x32_bf16 v[92:95], v[132:135], v[186:189], v[92:95]
	v_mfma_f32_16x16x32_bf16 v[88:91], v[150:153], v[182:185], v[88:91]
	v_mfma_f32_16x16x32_bf16 v[88:91], v[162:165], v[186:189], v[88:91]
	v_mfma_f32_16x16x32_bf16 v[28:31], v[166:169], v[182:185], v[28:31]
	v_mfma_f32_16x16x32_bf16 v[28:31], v[170:173], v[186:189], v[28:31]
	v_mfma_f32_16x16x32_bf16 v[24:27], v[174:177], v[182:185], v[24:27]
	v_mfma_f32_16x16x32_bf16 v[24:27], v[178:181], v[186:189], v[24:27]
	v_mfma_f32_16x16x32_bf16 v[16:19], v[174:177], v[190:193], v[16:19]
	v_mfma_f32_16x16x32_bf16 v[16:19], v[178:181], v[194:197], v[16:19]
	v_mfma_f32_16x16x32_bf16 v[20:23], v[166:169], v[190:193], v[20:23]
	v_mfma_f32_16x16x32_bf16 v[20:23], v[170:173], v[194:197], v[20:23]
	v_mfma_f32_16x16x32_bf16 v[80:83], v[150:153], v[190:193], v[80:83]
	v_mfma_f32_16x16x32_bf16 v[80:83], v[162:165], v[194:197], v[80:83]
	v_mfma_f32_16x16x32_bf16 v[84:87], v[128:131], v[190:193], v[84:87]
	v_mfma_f32_16x16x32_bf16 v[84:87], v[132:135], v[194:197], v[84:87]
	v_mfma_f32_16x16x32_bf16 v[76:79], v[128:131], v[198:201], v[76:79]
	v_mfma_f32_16x16x32_bf16 v[76:79], v[132:135], v[202:205], v[76:79]
	v_mfma_f32_16x16x32_bf16 v[72:75], v[150:153], v[198:201], v[72:75]
	v_mfma_f32_16x16x32_bf16 v[72:75], v[162:165], v[202:205], v[72:75]
	v_mfma_f32_16x16x32_bf16 v[12:15], v[166:169], v[198:201], v[12:15]
	v_mfma_f32_16x16x32_bf16 v[12:15], v[170:173], v[202:205], v[12:15]
	v_mfma_f32_16x16x32_bf16 v[8:11], v[174:177], v[198:201], v[8:11]
	v_mfma_f32_16x16x32_bf16 v[8:11], v[178:181], v[202:205], v[8:11]
	v_mfma_f32_16x16x32_bf16 v[0:3], v[174:177], v[206:209], v[0:3]
	v_mfma_f32_16x16x32_bf16 v[0:3], v[178:181], v[210:213], v[0:3]
	v_mfma_f32_16x16x32_bf16 v[4:7], v[166:169], v[206:209], v[4:7]
	v_mfma_f32_16x16x32_bf16 v[4:7], v[170:173], v[210:213], v[4:7]
	v_mfma_f32_16x16x32_bf16 v[56:59], v[150:153], v[206:209], v[56:59]
	v_mfma_f32_16x16x32_bf16 v[56:59], v[162:165], v[210:213], v[56:59]
	v_mfma_f32_16x16x32_bf16 v[60:63], v[128:131], v[206:209], v[60:63]
	v_mfma_f32_16x16x32_bf16 v[60:63], v[132:135], v[210:213], v[60:63]
	s_setprio 0
	s_waitcnt vmcnt(8)
	s_barrier
	s_add_i32 s59, s59, 2
	s_add_u32 s18, s18, 0x100
	s_addc_u32 s19, s19, 0
	s_add_u32 s57, s57, 0x100
	s_addc_u32 s58, s58, 0
	s_cmpk_gt_u32 s59, 0xfd
	s_cbranch_scc0 .LBB0_1321
	s_branch .Lf2_exit
; #define PG8_STAGE(bufoff, gbase, voff) do { _Pragma("unroll") for (int _i = 0; _i < 2; ++_i) \
;         __builtin_amdgcn_global_load_lds((const unsigned*)((const char*)(gbase) + (voff)[_i]), (PG8_LAS unsigned*)(lds + (bufoff) + ldsw + _i * 8192), 16, 0, 0); } while (0)
; #define PG8_LDA(dst, b, h) do { _Pragma("unroll") for (int m = 0; m < 4; ++m) _Pragma("unroll") for (int k = 0; k < 2; ++k) dst[m][k] = *(const PG8_LAS bf16x8*)(lds + PG8_SA(b, h) + aoff + m * 2048 + k * 1024); } while (0)
; #define PG8_LDB(dst, b, h) do { _Pragma("unroll") for (int n = 0; n < 2; ++n) _Pragma("unroll") for (int k = 0; k < 2; ++k) dst[n][k] = *(const PG8_LAS bf16x8*)(lds + PG8_SB(b, h) + boff + n * 2048 + k * 1024); } while (0)
; #define PG8_MMA(ai, bj, At, Bt) do { __builtin_amdgcn_s_setprio(1); _Pragma("unroll") for (int m = 0; m < 4; ++m) _Pragma("unroll") for (int n = 0; n < 2; ++n) _Pragma("unroll") for (int k = 0; k < 2; ++k) \
;         acc[ai][bj][m][n] = __builtin_amdgcn_mfma_f32_16x16x32_bf16(Bt[n][k], At[m][k], acc[ai][bj][m][n], 0, 0, 0); __builtin_amdgcn_s_setprio(0); } while (0)
; #define PG8_BAR __builtin_amdgcn_s_barrier()
; template <class Epi, class Sched, bool ALIGN_EPI = false, bool SP2 = false>
; __device__ __forceinline__ void gemm_phase(PG8_LAS unsigned char* lds, const Gemm g, const Sched& S, const Epi& E) {
;     ...
;             const bool last = (t == nt - 2);
;             const char* a1 = cA + (size_t)(t + 1) * kstep;
;             const char* a2 = last ? nA : cA + (size_t)(t + 2) * kstep; const char* b2 = last ? nB : cB + (size_t)(t + 2) * kstep;
;             const char* a3 = a2 + kstep; const char* b3 = b2 + kstep;
;             if (last && has_next) S.a_ready(nxt);
;             if constexpr (Epi::MIDK) { if (t == (nt >> 1)) { E.midk(acc, wr, fr); asm volatile("s_waitcnt lgkmcnt(0)" ::: "memory"); } }
;             if constexpr (SP2) {
;             PG8_LDB(B0, 0, 0); PG8_LDB(B1, 0, 1); PG8_SCHED; PG8_LDA(At, 0, 0); PG8_STAGE(PG8_SA(1, 1), a1 + hstep, voffA);
;             PG8_WAIT_V(8); PG8_WAIT_L(0); PG8_BAR; PG8_MMA(0, 0, At, B0); PG8_MMA(0, 1, At, B1); PG8_BAR; PG8_SCHED;
;             PG8_LDA(At, 0, 1); PG8_STAGE(PG8_SB(0, 0), b2, voffB); PG8_STAGE(PG8_SB(0, 1), b2 + hstep, voffB); PG8_STAGE(PG8_SA(0, 0), a2, voffA);
;             PG8_WAIT_V(8); PG8_WAIT_L(0); PG8_BAR; PG8_MMA(1, 0, At, B0); PG8_MMA(1, 1, At, B1); PG8_BAR; PG8_SCHED;
.Lf2_h1:
	ds_read_b128 v[128:131], v156
	ds_read_b128 v[132:135], v156 offset:1024
	ds_read_b128 v[150:153], v156 offset:2048
	ds_read_b128 v[162:165], v156 offset:3072
	ds_read_b128 v[166:169], v157
	ds_read_b128 v[170:173], v157 offset:1024
	ds_read_b128 v[174:177], v157 offset:2048
	ds_read_b128 v[178:181], v157 offset:3072
	s_add_u32 s20, s18, 0xffbfc080
	s_addc_u32 s21, s19, -1
	s_cmpk_eq_i32 s59, 0xfc
	s_cselect_b32 s23, s7, s21
	s_cselect_b32 s22, s6, s20
	s_cselect_b32 s21, s17, s58
	s_cselect_b32 s20, s16, s57
	ds_read_b128 v[182:185], v158
	ds_read_b128 v[186:189], v158 offset:1024
	ds_read_b128 v[190:193], v158 offset:2048
	ds_read_b128 v[194:197], v158 offset:3072
	ds_read_b128 v[198:201], v158 offset:4096
	ds_read_b128 v[202:205], v158 offset:5120
	ds_read_b128 v[206:209], v158 offset:6144
	ds_read_b128 v[210:213], v158 offset:7168
	s_add_i32 m0, s24, 0xc000
	s_nop 0
	global_load_lds_dwordx4 v136, s[18:19]
	s_add_i32 m0, s24, 0xe000
	s_nop 0
	global_load_lds_dwordx4 v140, s[18:19]
	s_sleep 2
	s_waitcnt lgkmcnt(0)
	s_waitcnt vmcnt(8)
	s_barrier
	s_setprio 2
	.p2align 3
	v_mfma_f32_16x16x32_bf16 v[124:127], v[128:131], v[182:185], v[124:127]
	v_mfma_f32_16x16x32_bf16 v[124:127], v[132:135], v[186:189], v[124:127]
	v_mfma_f32_16x16x32_bf16 v[120:123], v[150:153], v[182:185], v[120:123]
	v_mfma_f32_16x16x32_bf16 v[120:123], v[162:165], v[186:189], v[120:123]
	v_mfma_f32_16x16x32_bf16 v[68:71], v[166:169], v[182:185], v[68:71]
	v_mfma_f32_16x16x32_bf16 v[68:71], v[170:173], v[186:189], v[68:71]
	v_mfma_f32_16x16x32_bf16 v[64:67], v[174:177], v[182:185], v[64:67]
	v_mfma_f32_16x16x32_bf16 v[64:67], v[178:181], v[186:189], v[64:67]
	v_mfma_f32_16x16x32_bf16 v[48:51], v[174:177], v[190:193], v[48:51]
	v_mfma_f32_16x16x32_bf16 v[48:51], v[178:181], v[194:197], v[48:51]
	v_mfma_f32_16x16x32_bf16 v[52:55], v[166:169], v[190:193], v[52:55]
	v_mfma_f32_16x16x32_bf16 v[52:55], v[170:173], v[194:197], v[52:55]
	v_mfma_f32_16x16x32_bf16 v[112:115], v[150:153], v[190:193], v[112:115]
	v_mfma_f32_16x16x32_bf16 v[112:115], v[162:165], v[194:197], v[112:115]
	v_mfma_f32_16x16x32_bf16 v[116:119], v[128:131], v[190:193], v[116:119]
	v_mfma_f32_16x16x32_bf16 v[116:119], v[132:135], v[194:197], v[116:119]
	v_mfma_f32_16x16x32_bf16 v[108:111], v[128:131], v[198:201], v[108:111]
	v_mfma_f32_16x16x32_bf16 v[108:111], v[132:135], v[202:205], v[108:111]
	v_mfma_f32_16x16x32_bf16 v[104:107], v[150:153], v[198:201], v[104:107]
	v_mfma_f32_16x16x32_bf16 v[104:107], v[162:165], v[202:205], v[104:107]
	v_mfma_f32_16x16x32_bf16 v[44:47], v[166:169], v[198:201], v[44:47]
	v_mfma_f32_16x16x32_bf16 v[44:47], v[170:173], v[202:205], v[44:47]
	v_mfma_f32_16x16x32_bf16 v[40:43], v[174:177], v[198:201], v[40:43]
	v_mfma_f32_16x16x32_bf16 v[40:43], v[178:181], v[202:205], v[40:43]
	v_mfma_f32_16x16x32_bf16 v[32:35], v[174:177], v[206:209], v[32:35]
	v_mfma_f32_16x16x32_bf16 v[32:35], v[178:181], v[210:213], v[32:35]
	v_mfma_f32_16x16x32_bf16 v[36:39], v[166:169], v[206:209], v[36:39]
	v_mfma_f32_16x16x32_bf16 v[36:39], v[170:173], v[210:213], v[36:39]
	v_mfma_f32_16x16x32_bf16 v[96:99], v[150:153], v[206:209], v[96:99]
	v_mfma_f32_16x16x32_bf16 v[96:99], v[162:165], v[210:213], v[96:99]
	v_mfma_f32_16x16x32_bf16 v[100:103], v[128:131], v[206:209], v[100:103]
	v_mfma_f32_16x16x32_bf16 v[100:103], v[132:135], v[210:213], v[100:103]
	s_setprio 0
	ds_read_b128 v[182:185], v158 offset:16384
	ds_read_b128 v[186:189], v158 offset:17408
	ds_read_b128 v[190:193], v158 offset:18432
	ds_read_b128 v[194:197], v158 offset:19456
	ds_read_b128 v[198:201], v158 offset:20480
	ds_read_b128 v[202:205], v158 offset:21504
	ds_read_b128 v[206:209], v158 offset:22528
	ds_read_b128 v[210:213], v158 offset:23552
	s_add_u32 vcc_lo, s20, 0x404000
	s_addc_u32 vcc_hi, s21, 0
	s_add_i32 m0, s24, 0x10000
	s_nop 0
	global_load_lds_dwordx4 v138, s[20:21]
	s_add_i32 m0, s24, 0x12000
	s_nop 0
	global_load_lds_dwordx4 v142, s[20:21]
	s_add_i32 m0, s24, 0x14000
	s_nop 0
	global_load_lds_dwordx4 v138, vcc
	s_add_i32 m0, s24, 0x16000
	s_nop 0
	global_load_lds_dwordx4 v142, vcc
	s_mov_b32 m0, s24
	s_nop 0
	global_load_lds_dwordx4 v136, s[22:23]
	s_add_i32 m0, s24, 0x2000
	s_nop 0
	global_load_lds_dwordx4 v140, s[22:23]
	s_sleep 2
	s_waitcnt lgkmcnt(0)
	s_waitcnt vmcnt(8)
	s_barrier
; #define PG8_STAGE(bufoff, gbase, voff) do { _Pragma("unroll") for (int _i = 0; _i < 2; ++_i) \
;         __builtin_amdgcn_global_load_lds((const unsigned*)((const char*)(gbase) + (voff)[_i]), (PG8_LAS unsigned*)(lds + (bufoff) + ldsw + _i * 8192), 16, 0, 0); } while (0)
; #define PG8_LDA(dst, b, h) do { _Pragma("unroll") for (int m = 0; m < 4; ++m) _Pragma("unroll") for (int k = 0; k < 2; ++k) dst[m][k] = *(const PG8_LAS bf16x8*)(lds + PG8_SA(b, h) + aoff + m * 2048 + k * 1024); } while (0)
; #define PG8_LDB(dst, b, h) do { _Pragma("unroll") for (int n = 0; n < 2; ++n) _Pragma("unroll") for (int k = 0; k < 2; ++k) dst[n][k] = *(const PG8_LAS bf16x8*)(lds + PG8_SB(b, h) + boff + n * 2048 + k * 1024); } while (0)
; #define PG8_MMA(ai, bj, At, Bt) do { __builtin_amdgcn_s_setprio(1); _Pragma("unroll") for (int m = 0; m < 4; ++m) _Pragma("unroll") for (int n = 0; n < 2; ++n) _Pragma("unroll") for (int k = 0; k < 2; ++k) \
;         acc[ai][bj][m][n] = __builtin_amdgcn_mfma_f32_16x16x32_bf16(Bt[n][k], At[m][k], acc[ai][bj][m][n], 0, 0, 0); __builtin_amdgcn_s_setprio(0); } while (0)
; #define PG8_WAIT_V(n) asm volatile("s_waitcnt vmcnt(" #n ")" ::: "memory")
; #define PG8_WAIT_L(n) asm volatile("s_waitcnt lgkmcnt(" #n ")" ::: "memory")
; #define PG8_BAR __builtin_amdgcn_s_barrier()
; #define PG8_SCHED __builtin_amdgcn_sched_barrier(0)
; template <class Epi, class Sched, bool ALIGN_EPI = false, bool SP2 = false>
; __device__ __forceinline__ void gemm_phase(PG8_LAS unsigned char* lds, const Gemm g, const Sched& S, const Epi& E) {
;     ...
;             PG8_WAIT_V(8); PG8_WAIT_L(0); PG8_BAR; PG8_MMA(1, 0, At, B0); PG8_MMA(1, 1, At, B1); PG8_BAR; PG8_SCHED;
;             PG8_LDB(B0, 1, 0); PG8_LDB(B1, 1, 1); PG8_SCHED; PG8_LDA(At, 1, 0); PG8_STAGE(PG8_SA(0, 1), a2 + hstep, voffA);
;             PG8_WAIT_V(8); PG8_WAIT_L(0); PG8_BAR; PG8_MMA(0, 0, At, B0); PG8_MMA(0, 1, At, B1); PG8_BAR; PG8_SCHED;
	s_setprio 2
	.p2align 3
	v_mfma_f32_16x16x32_bf16 v[92:95], v[128:131], v[182:185], v[92:95]
	v_mfma_f32_16x16x32_bf16 v[92:95], v[132:135], v[186:189], v[92:95]
	v_mfma_f32_16x16x32_bf16 v[88:91], v[150:153], v[182:185], v[88:91]
	v_mfma_f32_16x16x32_bf16 v[88:91], v[162:165], v[186:189], v[88:91]
	v_mfma_f32_16x16x32_bf16 v[28:31], v[166:169], v[182:185], v[28:31]
	v_mfma_f32_16x16x32_bf16 v[28:31], v[170:173], v[186:189], v[28:31]
	v_mfma_f32_16x16x32_bf16 v[24:27], v[174:177], v[182:185], v[24:27]
	v_mfma_f32_16x16x32_bf16 v[24:27], v[178:181], v[186:189], v[24:27]
	v_mfma_f32_16x16x32_bf16 v[16:19], v[174:177], v[190:193], v[16:19]
	v_mfma_f32_16x16x32_bf16 v[16:19], v[178:181], v[194:197], v[16:19]
	v_mfma_f32_16x16x32_bf16 v[20:23], v[166:169], v[190:193], v[20:23]
	v_mfma_f32_16x16x32_bf16 v[20:23], v[170:173], v[194:197], v[20:23]
	v_mfma_f32_16x16x32_bf16 v[80:83], v[150:153], v[190:193], v[80:83]
	v_mfma_f32_16x16x32_bf16 v[80:83], v[162:165], v[194:197], v[80:83]
	v_mfma_f32_16x16x32_bf16 v[84:87], v[128:131], v[190:193], v[84:87]
	v_mfma_f32_16x16x32_bf16 v[84:87], v[132:135], v[194:197], v[84:87]
	v_mfma_f32_16x16x32_bf16 v[76:79], v[128:131], v[198:201], v[76:79]
	v_mfma_f32_16x16x32_bf16 v[76:79], v[132:135], v[202:205], v[76:79]
	v_mfma_f32_16x16x32_bf16 v[72:75], v[150:153], v[198:201], v[72:75]
	v_mfma_f32_16x16x32_bf16 v[72:75], v[162:165], v[202:205], v[72:75]
	v_mfma_f32_16x16x32_bf16 v[12:15], v[166:169], v[198:201], v[12:15]
	v_mfma_f32_16x16x32_bf16 v[12:15], v[170:173], v[202:205], v[12:15]
	v_mfma_f32_16x16x32_bf16 v[8:11], v[174:177], v[198:201], v[8:11]
	v_mfma_f32_16x16x32_bf16 v[8:11], v[178:181], v[202:205], v[8:11]
	v_mfma_f32_16x16x32_bf16 v[0:3], v[174:177], v[206:209], v[0:3]
	v_mfma_f32_16x16x32_bf16 v[0:3], v[178:181], v[210:213], v[0:3]
	v_mfma_f32_16x16x32_bf16 v[4:7], v[166:169], v[206:209], v[4:7]
	v_mfma_f32_16x16x32_bf16 v[4:7], v[170:173], v[210:213], v[4:7]
	v_mfma_f32_16x16x32_bf16 v[56:59], v[150:153], v[206:209], v[56:59]
	v_mfma_f32_16x16x32_bf16 v[56:59], v[162:165], v[210:213], v[56:59]
	v_mfma_f32_16x16x32_bf16 v[60:63], v[128:131], v[206:209], v[60:63]
	v_mfma_f32_16x16x32_bf16 v[60:63], v[132:135], v[210:213], v[60:63]
	s_setprio 0
	ds_read_b128 v[128:131], v159
	ds_read_b128 v[132:135], v159 offset:1024
	ds_read_b128 v[150:153], v159 offset:2048
	ds_read_b128 v[162:165], v159 offset:3072
	ds_read_b128 v[166:169], v160
	ds_read_b128 v[170:173], v160 offset:1024
	ds_read_b128 v[174:177], v160 offset:2048
	ds_read_b128 v[178:181], v160 offset:3072
	ds_read_b128 v[182:185], v158 offset:32768
	ds_read_b128 v[186:189], v158 offset:33792
	ds_read_b128 v[190:193], v158 offset:34816
	ds_read_b128 v[194:197], v158 offset:35840
	ds_read_b128 v[198:201], v158 offset:36864
	ds_read_b128 v[202:205], v158 offset:37888
	ds_read_b128 v[206:209], v158 offset:38912
	ds_read_b128 v[210:213], v158 offset:39936
	s_add_u32 vcc_lo, s22, 0x404000
	s_addc_u32 vcc_hi, s23, 0
	s_add_i32 m0, s24, 0x4000
	s_nop 0
	global_load_lds_dwordx4 v136, vcc
	s_add_i32 m0, s24, 0x6000
	s_nop 0
	global_load_lds_dwordx4 v140, vcc
	s_sleep 2
	s_waitcnt lgkmcnt(0)
	s_waitcnt vmcnt(8)
	s_barrier
; #define PG8_STAGE(bufoff, gbase, voff) do { _Pragma("unroll") for (int _i = 0; _i < 2; ++_i) \
;         __builtin_amdgcn_global_load_lds((const unsigned*)((const char*)(gbase) + (voff)[_i]), (PG8_LAS unsigned*)(lds + (bufoff) + ldsw + _i * 8192), 16, 0, 0); } while (0)
; #define PG8_LDA(dst, b, h) do { _Pragma("unroll") for (int m = 0; m < 4; ++m) _Pragma("unroll") for (int k = 0; k < 2; ++k) dst[m][k] = *(const PG8_LAS bf16x8*)(lds + PG8_SA(b, h) + aoff + m * 2048 + k * 1024); } while (0)
; #define PG8_WAIT_V(n) asm volatile("s_waitcnt vmcnt(" #n ")" ::: "memory")
; template <class Epi, class Sched, bool ALIGN_EPI = false, bool SP2 = false>
; __device__ __forceinline__ void gemm_phase(PG8_LAS unsigned char* lds, const Gemm g, const Sched& S, const Epi& E) {
;     ...
;         for (int t = 0; t < nt; t += 2) {
;             const bool last = (t == nt - 2);
;             const char* a1 = cA + (size_t)(t + 1) * kstep;
;             const char* a2 = last ? nA : cA + (size_t)(t + 2) * kstep; const char* b2 = last ? nB : cB + (size_t)(t + 2) * kstep;
;             const char* a3 = a2 + kstep; const char* b3 = b2 + kstep;
;             if (last && has_next) S.a_ready(nxt);
;             if constexpr (Epi::MIDK) { if (t == (nt >> 1)) { E.midk(acc, wr, fr); asm volatile("s_waitcnt lgkmcnt(0)" ::: "memory"); } }
;             if constexpr (SP2) {
;             PG8_LDB(B0, 0, 0); PG8_LDB(B1, 0, 1); PG8_SCHED; PG8_LDA(At, 0, 0); PG8_STAGE(PG8_SA(1, 1), a1 + hstep, voffA);
;             PG8_WAIT_V(8); PG8_WAIT_L(0); PG8_BAR; PG8_MMA(0, 0, At, B0); PG8_MMA(0, 1, At, B1); PG8_BAR; PG8_SCHED;
;             PG8_LDA(At, 0, 1); PG8_STAGE(PG8_SB(0, 0), b2, voffB); PG8_STAGE(PG8_SB(0, 1), b2 + hstep, voffB); PG8_STAGE(PG8_SA(0, 0), a2, voffA);
;             PG8_WAIT_V(8); PG8_WAIT_L(0); PG8_BAR; PG8_MMA(1, 0, At, B0); PG8_MMA(1, 1, At, B1); PG8_BAR; PG8_SCHED;
;             PG8_LDB(B0, 1, 0); PG8_LDB(B1, 1, 1); PG8_SCHED; PG8_LDA(At, 1, 0); PG8_STAGE(PG8_SA(0, 1), a2 + hstep, voffA);
;             PG8_WAIT_V(8); PG8_WAIT_L(0); PG8_BAR; PG8_MMA(0, 0, At, B0); PG8_MMA(0, 1, At, B1); PG8_BAR; PG8_SCHED;
;             PG8_LDA(At, 1, 1); PG8_STAGE(PG8_SB(1, 0), b3, voffB); PG8_STAGE(PG8_SB(1, 1), b3 + hstep, voffB); PG8_STAGE(PG8_SA(1, 0), a3, voffA);
;             PG8_WAIT_V(8); PG8_WAIT_L(0); PG8_BAR; PG8_MMA(1, 0, At, B0); PG8_MMA(1, 1, At, B1); PG8_BAR; PG8_SCHED;
	s_setprio 2
	.p2align 3
	v_mfma_f32_16x16x32_bf16 v[124:127], v[128:131], v[182:185], v[124:127]
	v_mfma_f32_16x16x32_bf16 v[124:127], v[132:135], v[186:189], v[124:127]
	v_mfma_f32_16x16x32_bf16 v[120:123], v[150:153], v[182:185], v[120:123]
	v_mfma_f32_16x16x32_bf16 v[120:123], v[162:165], v[186:189], v[120:123]
	v_mfma_f32_16x16x32_bf16 v[68:71], v[166:169], v[182:185], v[68:71]
	v_mfma_f32_16x16x32_bf16 v[68:71], v[170:173], v[186:189], v[68:71]
	v_mfma_f32_16x16x32_bf16 v[64:67], v[174:177], v[182:185], v[64:67]
	v_mfma_f32_16x16x32_bf16 v[64:67], v[178:181], v[186:189], v[64:67]
	v_mfma_f32_16x16x32_bf16 v[48:51], v[174:177], v[190:193], v[48:51]
	v_mfma_f32_16x16x32_bf16 v[48:51], v[178:181], v[194:197], v[48:51]
	v_mfma_f32_16x16x32_bf16 v[52:55], v[166:169], v[190:193], v[52:55]
	v_mfma_f32_16x16x32_bf16 v[52:55], v[170:173], v[194:197], v[52:55]
	v_mfma_f32_16x16x32_bf16 v[112:115], v[150:153], v[190:193], v[112:115]
	v_mfma_f32_16x16x32_bf16 v[112:115], v[162:165], v[194:197], v[112:115]
	v_mfma_f32_16x16x32_bf16 v[116:119], v[128:131], v[190:193], v[116:119]
	v_mfma_f32_16x16x32_bf16 v[116:119], v[132:135], v[194:197], v[116:119]
	v_mfma_f32_16x16x32_bf16 v[108:111], v[128:131], v[198:201], v[108:111]
	v_mfma_f32_16x16x32_bf16 v[108:111], v[132:135], v[202:205], v[108:111]
	v_mfma_f32_16x16x32_bf16 v[104:107], v[150:153], v[198:201], v[104:107]
	v_mfma_f32_16x16x32_bf16 v[104:107], v[162:165], v[202:205], v[104:107]
	v_mfma_f32_16x16x32_bf16 v[44:47], v[166:169], v[198:201], v[44:47]
	v_mfma_f32_16x16x32_bf16 v[44:47], v[170:173], v[202:205], v[44:47]
	v_mfma_f32_16x16x32_bf16 v[40:43], v[174:177], v[198:201], v[40:43]
	v_mfma_f32_16x16x32_bf16 v[40:43], v[178:181], v[202:205], v[40:43]
	v_mfma_f32_16x16x32_bf16 v[32:35], v[174:177], v[206:209], v[32:35]
	v_mfma_f32_16x16x32_bf16 v[32:35], v[178:181], v[210:213], v[32:35]
	v_mfma_f32_16x16x32_bf16 v[36:39], v[166:169], v[206:209], v[36:39]
	v_mfma_f32_16x16x32_bf16 v[36:39], v[170:173], v[210:213], v[36:39]
	v_mfma_f32_16x16x32_bf16 v[96:99], v[150:153], v[206:209], v[96:99]
	v_mfma_f32_16x16x32_bf16 v[96:99], v[162:165], v[210:213], v[96:99]
	v_mfma_f32_16x16x32_bf16 v[100:103], v[128:131], v[206:209], v[100:103]
	v_mfma_f32_16x16x32_bf16 v[100:103], v[132:135], v[210:213], v[100:103]
	s_setprio 0
	ds_read_b128 v[182:185], v158 offset:49152
	ds_read_b128 v[186:189], v158 offset:50176
	ds_read_b128 v[190:193], v158 offset:51200
	ds_read_b128 v[194:197], v158 offset:52224
	ds_read_b128 v[198:201], v158 offset:53248
	ds_read_b128 v[202:205], v158 offset:54272
	ds_read_b128 v[206:209], v158 offset:55296
	ds_read_b128 v[210:213], v158 offset:56320
	s_add_u32 s60, s20, 0x80
	s_addc_u32 s61, s21, 0
	s_add_u32 vcc_lo, s60, 0x404000
	s_addc_u32 vcc_hi, s61, 0
	s_add_i32 m0, s24, 0x18000
	s_nop 0
	global_load_lds_dwordx4 v138, s[60:61]
	s_add_i32 m0, s24, 0x1a000
	s_nop 0
	global_load_lds_dwordx4 v142, s[60:61]
	s_add_i32 m0, s24, 0x1c000
	s_nop 0
	global_load_lds_dwordx4 v138, vcc
	s_add_i32 m0, s24, 0x1e000
	s_nop 0
	global_load_lds_dwordx4 v142, vcc
	s_add_u32 s60, s22, 0x80
	s_addc_u32 s61, s23, 0
	s_add_i32 m0, s24, 0x8000
	s_nop 0
	global_load_lds_dwordx4 v136, s[60:61]
	s_add_i32 m0, s24, 0xa000
	s_nop 0
	global_load_lds_dwordx4 v140, s[60:61]
	s_sleep 2
	s_waitcnt lgkmcnt(0)
	s_waitcnt vmcnt(8)
	s_barrier
	s_setprio 2
	.p2align 3
	v_mfma_f32_16x16x32_bf16 v[92:95], v[128:131], v[182:185], v[92:95]
	v_mfma_f32_16x16x32_bf16 v[92:95], v[132:135], v[186:189], v[92:95]
	v_mfma_f32_16x16x32_bf16 v[88:91], v[150:153], v[182:185], v[88:91]
	v_mfma_f32_16x16x32_bf16 v[88:91], v[162:165], v[186:189], v[88:91]
	v_mfma_f32_16x16x32_bf16 v[28:31], v[166:169], v[182:185], v[28:31]
	v_mfma_f32_16x16x32_bf16 v[28:31], v[170:173], v[186:189], v[28:31]
	v_mfma_f32_16x16x32_bf16 v[24:27], v[174:177], v[182:185], v[24:27]
	v_mfma_f32_16x16x32_bf16 v[24:27], v[178:181], v[186:189], v[24:27]
	v_mfma_f32_16x16x32_bf16 v[16:19], v[174:177], v[190:193], v[16:19]
	v_mfma_f32_16x16x32_bf16 v[16:19], v[178:181], v[194:197], v[16:19]
	v_mfma_f32_16x16x32_bf16 v[20:23], v[166:169], v[190:193], v[20:23]
	v_mfma_f32_16x16x32_bf16 v[20:23], v[170:173], v[194:197], v[20:23]
	v_mfma_f32_16x16x32_bf16 v[80:83], v[150:153], v[190:193], v[80:83]
	v_mfma_f32_16x16x32_bf16 v[80:83], v[162:165], v[194:197], v[80:83]
	v_mfma_f32_16x16x32_bf16 v[84:87], v[128:131], v[190:193], v[84:87]
	v_mfma_f32_16x16x32_bf16 v[84:87], v[132:135], v[194:197], v[84:87]
	v_mfma_f32_16x16x32_bf16 v[76:79], v[128:131], v[198:201], v[76:79]
	v_mfma_f32_16x16x32_bf16 v[76:79], v[132:135], v[202:205], v[76:79]
	v_mfma_f32_16x16x32_bf16 v[72:75], v[150:153], v[198:201], v[72:75]
	v_mfma_f32_16x16x32_bf16 v[72:75], v[162:165], v[202:205], v[72:75]
	v_mfma_f32_16x16x32_bf16 v[12:15], v[166:169], v[198:201], v[12:15]
	v_mfma_f32_16x16x32_bf16 v[12:15], v[170:173], v[202:205], v[12:15]
	v_mfma_f32_16x16x32_bf16 v[8:11], v[174:177], v[198:201], v[8:11]
	v_mfma_f32_16x16x32_bf16 v[8:11], v[178:181], v[202:205], v[8:11]
	v_mfma_f32_16x16x32_bf16 v[0:3], v[174:177], v[206:209], v[0:3]
	v_mfma_f32_16x16x32_bf16 v[0:3], v[178:181], v[210:213], v[0:3]
	v_mfma_f32_16x16x32_bf16 v[4:7], v[166:169], v[206:209], v[4:7]
	v_mfma_f32_16x16x32_bf16 v[4:7], v[170:173], v[210:213], v[4:7]
	v_mfma_f32_16x16x32_bf16 v[56:59], v[150:153], v[206:209], v[56:59]
	v_mfma_f32_16x16x32_bf16 v[56:59], v[162:165], v[210:213], v[56:59]
	v_mfma_f32_16x16x32_bf16 v[60:63], v[128:131], v[206:209], v[60:63]
	v_mfma_f32_16x16x32_bf16 v[60:63], v[132:135], v[210:213], v[60:63]
	s_setprio 0
	s_add_i32 s59, s59, 2
	s_add_u32 s18, s18, 0x100
	s_addc_u32 s19, s19, 0
	s_add_u32 s57, s57, 0x100
	s_addc_u32 s58, s58, 0
	s_cmpk_gt_u32 s59, 0xfd
	s_cbranch_scc0 .Lf2_h1
